# plus attention output stage: norm-gain loads hoisted and batched, counted vmcnt (mem + neighbourhood attention)
# baseline (speedup 1.0000x reference)
.LBB0_117:
	v_mov_b32_e32 v16, v220
	s_ashr_i32 s3, s10, 8
	s_lshl_b32 s4, s3, 13
	s_and_b32 s5, s9, 0x1f80
	v_ashrrev_i32_e32 v0, 2, v16
	s_or_b32 s4, s4, s5
	v_and_b32_e32 v0, -16, v0
	v_and_b32_e32 v71, 15, v16
	v_add_u32_e32 v68, s4, v0
	s_lshl_b32 s3, s3, 2
	s_bfe_u32 s2, s10, 0x20006
	s_add_i32 s3, s3, s6
	v_or_b32_e32 v2, v68, v71
	s_waitcnt lgkmcnt(0)
	v_mov_b64_e32 v[0:1], s[64:65]
	v_bfe_u32 v70, v16, 4, 2
	s_or_b32 s4, s3, s2
	v_mad_i64_i32 v[0:1], s[12:13], v2, s96, v[0:1]
	s_lshl_b32 s92, s2, 8
	s_ashr_i32 s5, s4, 31
	v_lshl_add_u64 v[0:1], v[0:1], 0, s[92:93]
	v_lshlrev_b32_e32 v176, 4, v70
	v_lshl_add_u64 v[0:1], v[0:1], 0, v[176:177]
	s_mov_b64 s[12:13], 0x2400
	s_lshl_b64 s[4:5], s[4:5], 16
	v_lshl_add_u64 v[2:3], v[0:1], 0, s[12:13]
	s_add_u32 s12, s24, s4
	v_ashrrev_i32_e32 v17, 31, v16
	v_add_co_u32_e32 v0, vcc, s31, v0
	s_addc_u32 s13, s25, s5
	v_lshlrev_b64 v[24:25], 4, v[16:17]
	v_addc_co_u32_e32 v1, vcc, 0, v1, vcc
	v_lshl_add_u64 v[80:81], s[12:13], 0, v[24:25]
	global_load_dwordx4 v[12:15], v[0:1], off offset:1024
	global_load_dwordx4 v[8:11], v[2:3], off offset:64
	global_load_dwordx4 v[4:7], v[2:3], off offset:128
	s_nop 0
	global_load_dwordx4 v[0:3], v[2:3], off offset:192
	s_add_u32 s4, s26, s4
	global_load_dwordx4 v[20:23], v[80:81], off
	s_addc_u32 s5, s27, s5
	v_lshl_add_u64 v[84:85], s[4:5], 0, v[24:25]
	global_load_dwordx4 v[24:27], v[84:85], off
	v_add_co_u32_e32 v28, vcc, s31, v80
	v_lshrrev_b32_e32 v92, 5, v16
	s_nop 0
	v_addc_co_u32_e32 v29, vcc, 0, v81, vcc
	global_load_dwordx4 v[28:31], v[28:29], off
	v_add_co_u32_e32 v32, vcc, s31, v84
	v_ashrrev_i32_e32 v94, 4, v16
	s_nop 0
	v_addc_co_u32_e32 v33, vcc, 0, v85, vcc
	global_load_dwordx4 v[32:35], v[32:33], off
	v_add_co_u32_e32 v36, vcc, s34, v80
	v_and_b32_e32 v92, 12, v92
	s_nop 0
	v_addc_co_u32_e32 v37, vcc, 0, v81, vcc
	global_load_dwordx4 v[36:39], v[36:37], off
	v_add_co_u32_e32 v40, vcc, s34, v84
	v_and_b32_e32 v95, 3, v94
	s_nop 0
	v_addc_co_u32_e32 v41, vcc, 0, v85, vcc
	global_load_dwordx4 v[40:43], v[40:41], off
	v_add_co_u32_e32 v44, vcc, s35, v80
	v_bitop3_b32 v95, v95, v71, v92 bitop3:0x36
	s_nop 0
	v_addc_co_u32_e32 v45, vcc, 0, v81, vcc
	global_load_dwordx4 v[44:47], v[44:45], off
	v_add_co_u32_e32 v48, vcc, s35, v84
	v_lshlrev_b32_e32 v94, 8, v94
	s_nop 0
	v_addc_co_u32_e32 v49, vcc, 0, v85, vcc
	global_load_dwordx4 v[48:51], v[48:49], off
	v_add_co_u32_e32 v52, vcc, s11, v80
	v_lshlrev_b32_e32 v95, 4, v95
	s_nop 0
	v_addc_co_u32_e32 v53, vcc, 0, v81, vcc
	global_load_dwordx4 v[52:55], v[52:53], off
	v_add_co_u32_e32 v56, vcc, s11, v84
	v_add3_u32 v94, 0, v94, v95
	s_nop 0
	v_addc_co_u32_e32 v57, vcc, 0, v85, vcc
	global_load_dwordx4 v[56:59], v[56:57], off
	v_add_co_u32_e32 v60, vcc, s14, v80
	v_and_b32_e32 v93, 31, v16
	s_nop 0
	v_addc_co_u32_e32 v61, vcc, 0, v81, vcc
	global_load_dwordx4 v[60:63], v[60:61], off
	v_add_co_u32_e32 v64, vcc, s14, v84
	s_add_i32 s3, 0, 0x10000
	s_nop 0
	v_addc_co_u32_e32 v65, vcc, 0, v85, vcc
	global_load_dwordx4 v[64:67], v[64:65], off
	v_add_co_u32_e32 v72, vcc, s15, v80
	v_add_u32_e32 v17, 0x200, v16
	s_nop 0
	v_addc_co_u32_e32 v73, vcc, 0, v81, vcc
	global_load_dwordx4 v[72:75], v[72:73], off
	v_add_co_u32_e32 v76, vcc, s15, v84
	v_add_u32_e32 v19, 0x400, v16
	s_nop 0
	v_addc_co_u32_e32 v77, vcc, 0, v85, vcc
	global_load_dwordx4 v[76:79], v[76:77], off
	v_add_co_u32_e32 v80, vcc, s16, v80
	v_add_u32_e32 v69, 0x600, v16
	s_nop 0
	v_addc_co_u32_e32 v81, vcc, 0, v81, vcc
	global_load_dwordx4 v[80:83], v[80:81], off
	v_add_co_u32_e32 v84, vcc, s16, v84
	v_add_u32_e32 v88, 0x800, v16
	s_nop 0
	v_addc_co_u32_e32 v85, vcc, 0, v85, vcc
	global_load_dwordx4 v[84:87], v[84:85], off
	s_waitcnt vmcnt(0) lgkmcnt(0)
	s_barrier
	ds_write_b128 v94, v[20:23]
	v_ashrrev_i32_e32 v20, 5, v16
	v_lshlrev_b32_e32 v21, 9, v20
	v_bitop3_b32 v20, v20, v93, 15 bitop3:0x6c
	v_lshlrev_b32_e32 v20, 4, v20
	v_add3_u32 v20, s3, v21, v20
	ds_write_b128 v20, v[24:27]
	v_ashrrev_i32_e32 v20, 4, v17
	v_and_b32_e32 v21, 3, v20
	v_bitop3_b32 v21, v21, v71, v92 bitop3:0x36
	v_lshlrev_b32_e32 v20, 8, v20
	v_lshlrev_b32_e32 v21, 4, v21
	v_add3_u32 v20, 0, v20, v21
	v_ashrrev_i32_e32 v17, 5, v17
	ds_write_b128 v20, v[28:31]
	v_lshlrev_b32_e32 v20, 9, v17
	v_bitop3_b32 v17, v17, v93, 15 bitop3:0x6c
	v_lshlrev_b32_e32 v17, 4, v17
	v_add3_u32 v17, s3, v20, v17
	ds_write_b128 v17, v[32:35]
	v_ashrrev_i32_e32 v17, 4, v19
	v_and_b32_e32 v20, 3, v17
	v_bitop3_b32 v20, v20, v71, v92 bitop3:0x36
	v_lshlrev_b32_e32 v17, 8, v17
	v_lshlrev_b32_e32 v20, 4, v20
	v_add3_u32 v17, 0, v17, v20
	ds_write_b128 v17, v[36:39]
	v_ashrrev_i32_e32 v17, 5, v19
	v_lshlrev_b32_e32 v19, 9, v17
	v_bitop3_b32 v17, v17, v93, 15 bitop3:0x6c
	v_lshlrev_b32_e32 v17, 4, v17
	v_add3_u32 v17, s3, v19, v17
	ds_write_b128 v17, v[40:43]
	v_ashrrev_i32_e32 v17, 4, v69
	v_and_b32_e32 v19, 3, v17
	v_bitop3_b32 v19, v19, v71, v92 bitop3:0x36
	v_lshlrev_b32_e32 v17, 8, v17
	v_lshlrev_b32_e32 v19, 4, v19
	v_add3_u32 v17, 0, v17, v19
	ds_write_b128 v17, v[44:47]
	v_ashrrev_i32_e32 v17, 5, v69
	v_lshlrev_b32_e32 v19, 9, v17
	v_bitop3_b32 v17, v17, v93, 15 bitop3:0x6c
	v_lshlrev_b32_e32 v17, 4, v17
	v_add3_u32 v17, s3, v19, v17
	ds_write_b128 v17, v[48:51]
	v_ashrrev_i32_e32 v17, 4, v88
	v_and_b32_e32 v19, 3, v17
	v_bitop3_b32 v19, v19, v71, v92 bitop3:0x36
	v_lshlrev_b32_e32 v17, 8, v17
	v_lshlrev_b32_e32 v19, 4, v19
	v_add3_u32 v17, 0, v17, v19
	ds_write_b128 v17, v[52:55]
	v_ashrrev_i32_e32 v17, 5, v88
	v_lshlrev_b32_e32 v19, 9, v17
	v_bitop3_b32 v17, v17, v93, 15 bitop3:0x6c
	v_lshlrev_b32_e32 v17, 4, v17
	v_add_u32_e32 v89, 0xa00, v16
	v_add3_u32 v17, s3, v19, v17
	ds_write_b128 v17, v[56:59]
	v_ashrrev_i32_e32 v17, 4, v89
	v_and_b32_e32 v19, 3, v17
	v_bitop3_b32 v19, v19, v71, v92 bitop3:0x36
	v_lshlrev_b32_e32 v17, 8, v17
	v_lshlrev_b32_e32 v19, 4, v19
	v_add3_u32 v17, 0, v17, v19
	ds_write_b128 v17, v[60:63]
	v_ashrrev_i32_e32 v17, 5, v89
	v_lshlrev_b32_e32 v19, 9, v17
	v_bitop3_b32 v17, v17, v93, 15 bitop3:0x6c
	v_lshlrev_b32_e32 v17, 4, v17
	v_add_u32_e32 v90, 0xc00, v16
	v_add3_u32 v17, s3, v19, v17
	ds_write_b128 v17, v[64:67]
	v_ashrrev_i32_e32 v17, 4, v90
	v_and_b32_e32 v19, 3, v17
	v_bitop3_b32 v19, v19, v71, v92 bitop3:0x36
	v_lshlrev_b32_e32 v17, 8, v17
	v_lshlrev_b32_e32 v19, 4, v19
	v_add3_u32 v17, 0, v17, v19
	ds_write_b128 v17, v[72:75]
	v_ashrrev_i32_e32 v17, 5, v90
	v_lshlrev_b32_e32 v19, 9, v17
	v_bitop3_b32 v17, v17, v93, 15 bitop3:0x6c
	v_lshlrev_b32_e32 v17, 4, v17
	v_add_u32_e32 v91, 0xe00, v16
	v_add3_u32 v17, s3, v19, v17
	ds_write_b128 v17, v[76:79]
	v_ashrrev_i32_e32 v17, 4, v91
	v_and_b32_e32 v19, 3, v17
	v_bitop3_b32 v19, v19, v71, v92 bitop3:0x36
	v_lshlrev_b32_e32 v17, 8, v17
	v_lshlrev_b32_e32 v19, 4, v19
	v_add3_u32 v17, 0, v17, v19
	ds_write_b128 v17, v[80:83]
	v_ashrrev_i32_e32 v17, 5, v91
	v_lshlrev_b32_e32 v19, 9, v17
	v_bitop3_b32 v17, v17, v93, 15 bitop3:0x6c
	v_lshlrev_b32_e32 v17, 4, v17
	v_add3_u32 v17, s3, v19, v17
	v_and_b32_e32 v19, 0xffff0000, v12
	ds_write_b128 v17, v[84:87]
	v_lshlrev_b32_e32 v17, 16, v12
	v_mul_f32_e32 v19, v19, v19
	v_and_b32_e32 v20, 0xffff0000, v13
	v_fmac_f32_e32 v19, v17, v17
	v_lshlrev_b32_e32 v17, 16, v13
	v_mul_f32_e32 v20, v20, v20
	v_fmac_f32_e32 v20, v17, v17
	v_add_f32_e32 v17, v19, v20
	v_and_b32_e32 v20, 0xffff0000, v14
	v_lshlrev_b32_e32 v19, 16, v14
	v_mul_f32_e32 v20, v20, v20
	v_fmac_f32_e32 v20, v19, v19
	v_add_f32_e32 v17, v20, v17
	v_and_b32_e32 v20, 0xffff0000, v15
	v_lshlrev_b32_e32 v19, 16, v15
	v_mul_f32_e32 v20, v20, v20
	v_fmac_f32_e32 v20, v19, v19
	v_add_f32_e32 v17, v20, v17
	v_and_b32_e32 v20, 0xffff0000, v8
	v_lshlrev_b32_e32 v19, 16, v8
	v_mul_f32_e32 v20, v20, v20
	v_fmac_f32_e32 v20, v19, v19
	v_add_f32_e32 v17, v20, v17
	v_and_b32_e32 v20, 0xffff0000, v9
	v_lshlrev_b32_e32 v19, 16, v9
	v_mul_f32_e32 v20, v20, v20
	v_fmac_f32_e32 v20, v19, v19
	v_add_f32_e32 v17, v20, v17
	v_and_b32_e32 v20, 0xffff0000, v10
	v_lshlrev_b32_e32 v19, 16, v10
	v_mul_f32_e32 v20, v20, v20
	v_fmac_f32_e32 v20, v19, v19
	v_add_f32_e32 v17, v20, v17
	v_and_b32_e32 v20, 0xffff0000, v11
	v_lshlrev_b32_e32 v19, 16, v11
	v_mul_f32_e32 v20, v20, v20
	v_fmac_f32_e32 v20, v19, v19
	v_and_b32_e32 v23, 0xffff0000, v5
	v_and_b32_e32 v22, 0xffff0000, v4
	v_add_f32_e32 v17, v20, v17
	v_lshlrev_b32_e32 v21, 16, v5
	v_lshlrev_b32_e32 v20, 16, v4
	v_pk_mul_f32 v[22:23], v[22:23], v[22:23]
	v_xor_b32_e32 v19, 16, v225
	v_pk_fma_f32 v[20:21], v[20:21], v[20:21], v[22:23]
	v_and_b32_e32 v23, 0xffff0000, v7
	v_add_f32_e32 v17, v20, v17
	v_and_b32_e32 v22, 0xffff0000, v6
	v_add_f32_e32 v17, v21, v17
	v_lshlrev_b32_e32 v21, 16, v7
	v_lshlrev_b32_e32 v20, 16, v6
	v_pk_mul_f32 v[22:23], v[22:23], v[22:23]
	v_lshrrev_b32_e32 v18, 4, v16
	v_pk_fma_f32 v[20:21], v[20:21], v[20:21], v[22:23]
	v_and_b32_e32 v23, 0xffff0000, v1
	v_add_f32_e32 v17, v20, v17
	v_and_b32_e32 v22, 0xffff0000, v0
	v_add_f32_e32 v17, v21, v17
	v_lshlrev_b32_e32 v21, 16, v1
	v_lshlrev_b32_e32 v20, 16, v0
	v_pk_mul_f32 v[22:23], v[22:23], v[22:23]
	v_lshlrev_b32_e32 v72, 1, v71
	v_pk_fma_f32 v[20:21], v[20:21], v[20:21], v[22:23]
	v_and_b32_e32 v23, 0xffff0000, v3
	v_add_f32_e32 v17, v20, v17
	v_and_b32_e32 v22, 0xffff0000, v2
	v_add_f32_e32 v17, v21, v17
	v_lshlrev_b32_e32 v21, 16, v3
	v_lshlrev_b32_e32 v20, 16, v2
	v_pk_mul_f32 v[22:23], v[22:23], v[22:23]
	v_and_b32_e32 v16, 3, v16
	v_pk_fma_f32 v[20:21], v[20:21], v[20:21], v[22:23]
	v_and_or_b32 v16, v72, 24, v16
	v_add_f32_e32 v17, v20, v17
	v_and_b32_e32 v20, 64, v225
	v_add_u32_e32 v69, 64, v20
	v_cmp_lt_i32_e32 vcc, v19, v69
	v_add_f32_e32 v17, v21, v17
	v_lshl_add_u32 v24, v16, 8, 0
	v_cndmask_b32_e32 v19, v225, v19, vcc
	v_lshlrev_b32_e32 v75, 2, v19
	ds_bpermute_b32 v19, v75, v17
	s_waitcnt lgkmcnt(0)
	s_barrier
	v_bitop3_b32 v20, v70, v71, 4 bitop3:0x36
	v_add_f32_e32 v17, v17, v19
	v_xor_b32_e32 v19, 32, v225
	v_cmp_lt_i32_e32 vcc, v19, v69
	v_lshlrev_b32_e32 v76, 4, v20
	v_add_u32_e32 v94, v24, v76
	v_cndmask_b32_e32 v19, v225, v19, vcc
	v_lshlrev_b32_e32 v78, 2, v19
	ds_bpermute_b32 v19, v78, v17
	ds_read_b128 v[20:23], v94
	s_lshl_b32 s2, s2, 9
	s_add_u32 s2, s7, s2
	v_lshl_or_b32 v176, v70, 14, v72
	s_waitcnt lgkmcnt(1)
	v_add_f32_e32 v17, v17, v19
	v_fmamk_f32 v17, v17, 0x3c000000, v222
	v_cmp_gt_f32_e32 vcc, s33, v17
	v_mul_f32_e32 v19, 0x4b800000, v17
	ds_read_b128 v[88:91], v94 offset:57344
	v_cndmask_b32_e32 v17, v17, v19, vcc
	v_rsq_f32_e32 v79, v17
	v_bitop3_b32 v17, v18, v71, 3 bitop3:0x6c
	v_lshlrev_b32_e32 v77, 4, v17
	v_add_u32_e32 v93, v24, v77
	ds_read_b128 v[16:19], v93
	s_waitcnt lgkmcnt(0)
	v_mfma_f32_16x16x32_bf16 v[16:19], v[16:19], v[12:15], 0
	v_mul_f32_e32 v92, 0x45800000, v79
	v_cndmask_b32_e32 v79, v79, v92, vcc
	v_mfma_f32_16x16x32_bf16 v[16:19], v[20:23], v[8:11], v[16:19]
	v_bitop3_b32 v20, v70, v71, 8 bitop3:0x36
	v_lshlrev_b32_e32 v74, 4, v20
	v_add_u32_e32 v95, v24, v74
	ds_read_b128 v[20:23], v95
	s_waitcnt lgkmcnt(0)
	v_mfma_f32_16x16x32_bf16 v[16:19], v[20:23], v[4:7], v[16:19]
	v_bitop3_b32 v20, v70, v71, 12 bitop3:0x36
	v_lshlrev_b32_e32 v73, 4, v20
	v_add_u32_e32 v96, v24, v73
	ds_read_b128 v[20:23], v96
	s_waitcnt lgkmcnt(0)
	v_mfma_f32_16x16x32_bf16 v[80:83], v[20:23], v[0:3], v[16:19]
	s_nop 2
	ds_read_b128 v[16:19], v93 offset:1024
	ds_read_b128 v[20:23], v94 offset:1024
	s_waitcnt lgkmcnt(1)
	v_mfma_f32_16x16x32_bf16 v[16:19], v[16:19], v[12:15], 0
	s_waitcnt lgkmcnt(0)
	v_mfma_f32_16x16x32_bf16 v[16:19], v[20:23], v[8:11], v[16:19]
	ds_read_b128 v[20:23], v95 offset:1024
	s_waitcnt lgkmcnt(0)
	v_mfma_f32_16x16x32_bf16 v[16:19], v[20:23], v[4:7], v[16:19]
	ds_read_b128 v[20:23], v96 offset:1024
	s_waitcnt lgkmcnt(0)
	v_mfma_f32_16x16x32_bf16 v[84:87], v[20:23], v[0:3], v[16:19]
	s_nop 4
	ds_read_b128 v[16:19], v93 offset:8192
	ds_read_b128 v[20:23], v94 offset:8192
	s_waitcnt lgkmcnt(1)
	v_mfma_f32_16x16x32_bf16 v[16:19], v[16:19], v[12:15], 0
	s_waitcnt lgkmcnt(0)
	v_mfma_f32_16x16x32_bf16 v[16:19], v[20:23], v[8:11], v[16:19]
	ds_read_b128 v[20:23], v95 offset:8192
	s_waitcnt lgkmcnt(0)
	v_mfma_f32_16x16x32_bf16 v[16:19], v[20:23], v[4:7], v[16:19]
	ds_read_b128 v[20:23], v96 offset:8192
	s_waitcnt lgkmcnt(0)
	v_mfma_f32_16x16x32_bf16 v[64:67], v[20:23], v[0:3], v[16:19]
	s_nop 4
	ds_read_b128 v[16:19], v93 offset:9216
	ds_read_b128 v[20:23], v94 offset:9216
	s_waitcnt lgkmcnt(1)
	v_mfma_f32_16x16x32_bf16 v[16:19], v[16:19], v[12:15], 0
	s_waitcnt lgkmcnt(0)
	v_mfma_f32_16x16x32_bf16 v[16:19], v[20:23], v[8:11], v[16:19]
	ds_read_b128 v[20:23], v95 offset:9216
	s_waitcnt lgkmcnt(0)
	v_mfma_f32_16x16x32_bf16 v[16:19], v[20:23], v[4:7], v[16:19]
	ds_read_b128 v[20:23], v96 offset:9216
	s_waitcnt lgkmcnt(0)
	v_mfma_f32_16x16x32_bf16 v[60:63], v[20:23], v[0:3], v[16:19]
	s_nop 4
	ds_read_b128 v[16:19], v93 offset:16384
	ds_read_b128 v[20:23], v94 offset:16384
	s_waitcnt lgkmcnt(1)
	v_mfma_f32_16x16x32_bf16 v[16:19], v[16:19], v[12:15], 0
	s_waitcnt lgkmcnt(0)
	v_mfma_f32_16x16x32_bf16 v[16:19], v[20:23], v[8:11], v[16:19]
	ds_read_b128 v[20:23], v95 offset:16384
	s_waitcnt lgkmcnt(0)
	v_mfma_f32_16x16x32_bf16 v[16:19], v[20:23], v[4:7], v[16:19]
	ds_read_b128 v[20:23], v96 offset:16384
	s_waitcnt lgkmcnt(0)
	v_mfma_f32_16x16x32_bf16 v[56:59], v[20:23], v[0:3], v[16:19]
	s_nop 4
	ds_read_b128 v[16:19], v93 offset:17408
	ds_read_b128 v[20:23], v94 offset:17408
	s_waitcnt lgkmcnt(1)
	v_mfma_f32_16x16x32_bf16 v[16:19], v[16:19], v[12:15], 0
	s_waitcnt lgkmcnt(0)
	v_mfma_f32_16x16x32_bf16 v[16:19], v[20:23], v[8:11], v[16:19]
	ds_read_b128 v[20:23], v95 offset:17408
	s_waitcnt lgkmcnt(0)
	v_mfma_f32_16x16x32_bf16 v[16:19], v[20:23], v[4:7], v[16:19]
	ds_read_b128 v[20:23], v96 offset:17408
	s_waitcnt lgkmcnt(0)
	v_mfma_f32_16x16x32_bf16 v[52:55], v[20:23], v[0:3], v[16:19]
	s_nop 4
	ds_read_b128 v[16:19], v93 offset:24576
	ds_read_b128 v[20:23], v94 offset:24576
	s_waitcnt lgkmcnt(1)
	v_mfma_f32_16x16x32_bf16 v[16:19], v[16:19], v[12:15], 0
	s_waitcnt lgkmcnt(0)
	v_mfma_f32_16x16x32_bf16 v[16:19], v[20:23], v[8:11], v[16:19]
	ds_read_b128 v[20:23], v95 offset:24576
	s_waitcnt lgkmcnt(0)
	v_mfma_f32_16x16x32_bf16 v[16:19], v[20:23], v[4:7], v[16:19]
	ds_read_b128 v[20:23], v96 offset:24576
	s_waitcnt lgkmcnt(0)
	v_mfma_f32_16x16x32_bf16 v[48:51], v[20:23], v[0:3], v[16:19]
	s_nop 4
	ds_read_b128 v[16:19], v93 offset:25600
	ds_read_b128 v[20:23], v94 offset:25600
	s_waitcnt lgkmcnt(1)
	v_mfma_f32_16x16x32_bf16 v[16:19], v[16:19], v[12:15], 0
	s_waitcnt lgkmcnt(0)
	v_mfma_f32_16x16x32_bf16 v[16:19], v[20:23], v[8:11], v[16:19]
	ds_read_b128 v[20:23], v95 offset:25600
	s_waitcnt lgkmcnt(0)
	v_mfma_f32_16x16x32_bf16 v[16:19], v[20:23], v[4:7], v[16:19]
	ds_read_b128 v[20:23], v96 offset:25600
	s_waitcnt lgkmcnt(0)
	v_mfma_f32_16x16x32_bf16 v[44:47], v[20:23], v[0:3], v[16:19]
	s_nop 4
	ds_read_b128 v[16:19], v93 offset:32768
	ds_read_b128 v[20:23], v94 offset:32768
	s_waitcnt lgkmcnt(1)
	v_mfma_f32_16x16x32_bf16 v[16:19], v[16:19], v[12:15], 0
	s_waitcnt lgkmcnt(0)
	v_mfma_f32_16x16x32_bf16 v[16:19], v[20:23], v[8:11], v[16:19]
	ds_read_b128 v[20:23], v95 offset:32768
	s_waitcnt lgkmcnt(0)
	v_mfma_f32_16x16x32_bf16 v[16:19], v[20:23], v[4:7], v[16:19]
	ds_read_b128 v[20:23], v96 offset:32768
	s_waitcnt lgkmcnt(0)
	v_mfma_f32_16x16x32_bf16 v[40:43], v[20:23], v[0:3], v[16:19]
	s_nop 4
	ds_read_b128 v[16:19], v93 offset:33792
	ds_read_b128 v[20:23], v94 offset:33792
	s_waitcnt lgkmcnt(1)
	v_mfma_f32_16x16x32_bf16 v[16:19], v[16:19], v[12:15], 0
	s_waitcnt lgkmcnt(0)
	v_mfma_f32_16x16x32_bf16 v[16:19], v[20:23], v[8:11], v[16:19]
	ds_read_b128 v[20:23], v95 offset:33792
	s_waitcnt lgkmcnt(0)
	v_mfma_f32_16x16x32_bf16 v[16:19], v[20:23], v[4:7], v[16:19]
	ds_read_b128 v[20:23], v96 offset:33792
	s_waitcnt lgkmcnt(0)
	v_mfma_f32_16x16x32_bf16 v[36:39], v[20:23], v[0:3], v[16:19]
	s_nop 4
	ds_read_b128 v[16:19], v93 offset:40960
	ds_read_b128 v[20:23], v94 offset:40960
	s_waitcnt lgkmcnt(1)
	v_mfma_f32_16x16x32_bf16 v[16:19], v[16:19], v[12:15], 0
	s_waitcnt lgkmcnt(0)
	v_mfma_f32_16x16x32_bf16 v[16:19], v[20:23], v[8:11], v[16:19]
	ds_read_b128 v[20:23], v95 offset:40960
	s_waitcnt lgkmcnt(0)
	v_mfma_f32_16x16x32_bf16 v[16:19], v[20:23], v[4:7], v[16:19]
	ds_read_b128 v[20:23], v96 offset:40960
	s_waitcnt lgkmcnt(0)
	v_mfma_f32_16x16x32_bf16 v[32:35], v[20:23], v[0:3], v[16:19]
	s_nop 4
	ds_read_b128 v[16:19], v93 offset:41984
	ds_read_b128 v[20:23], v94 offset:41984
	s_waitcnt lgkmcnt(1)
	v_mfma_f32_16x16x32_bf16 v[16:19], v[16:19], v[12:15], 0
	s_waitcnt lgkmcnt(0)
	v_mfma_f32_16x16x32_bf16 v[16:19], v[20:23], v[8:11], v[16:19]
	ds_read_b128 v[20:23], v95 offset:41984
	s_waitcnt lgkmcnt(0)
	v_mfma_f32_16x16x32_bf16 v[16:19], v[20:23], v[4:7], v[16:19]
	ds_read_b128 v[20:23], v96 offset:41984
	s_waitcnt lgkmcnt(0)
	v_mfma_f32_16x16x32_bf16 v[28:31], v[20:23], v[0:3], v[16:19]
	s_nop 4
	ds_read_b128 v[16:19], v93 offset:49152
	ds_read_b128 v[20:23], v94 offset:49152
	s_waitcnt lgkmcnt(1)
	v_mfma_f32_16x16x32_bf16 v[16:19], v[16:19], v[12:15], 0
	s_waitcnt lgkmcnt(0)
	v_mfma_f32_16x16x32_bf16 v[16:19], v[20:23], v[8:11], v[16:19]
	ds_read_b128 v[20:23], v95 offset:49152
	s_waitcnt lgkmcnt(0)
	v_mfma_f32_16x16x32_bf16 v[16:19], v[20:23], v[4:7], v[16:19]
	ds_read_b128 v[20:23], v96 offset:49152
	s_waitcnt lgkmcnt(0)
	v_mfma_f32_16x16x32_bf16 v[24:27], v[20:23], v[0:3], v[16:19]
	s_nop 4
	ds_read_b128 v[16:19], v93 offset:50176
	ds_read_b128 v[20:23], v94 offset:50176
	s_waitcnt lgkmcnt(1)
	v_mfma_f32_16x16x32_bf16 v[16:19], v[16:19], v[12:15], 0
	s_waitcnt lgkmcnt(0)
	v_mfma_f32_16x16x32_bf16 v[16:19], v[20:23], v[8:11], v[16:19]
	ds_read_b128 v[20:23], v95 offset:50176
	s_waitcnt lgkmcnt(0)
	v_mfma_f32_16x16x32_bf16 v[16:19], v[20:23], v[4:7], v[16:19]
	ds_read_b128 v[20:23], v96 offset:50176
	s_waitcnt lgkmcnt(0)
	v_mfma_f32_16x16x32_bf16 v[20:23], v[20:23], v[0:3], v[16:19]
	s_nop 4
	ds_read_b128 v[16:19], v93 offset:57344
	s_waitcnt lgkmcnt(0)
	v_mfma_f32_16x16x32_bf16 v[16:19], v[16:19], v[12:15], 0
	v_mfma_f32_16x16x32_bf16 v[16:19], v[88:91], v[8:11], v[16:19]
	ds_read_b128 v[88:91], v95 offset:57344
	s_waitcnt lgkmcnt(0)
	v_mfma_f32_16x16x32_bf16 v[16:19], v[88:91], v[4:7], v[16:19]
	ds_read_b128 v[88:91], v96 offset:57344
	s_waitcnt lgkmcnt(0)
	v_mfma_f32_16x16x32_bf16 v[16:19], v[88:91], v[0:3], v[16:19]
	ds_read_b128 v[88:91], v93 offset:58368
	s_waitcnt lgkmcnt(0)
	v_mfma_f32_16x16x32_bf16 v[12:15], v[88:91], v[12:15], 0
	ds_read_b128 v[88:91], v94 offset:58368
	s_waitcnt lgkmcnt(0)
	v_mfma_f32_16x16x32_bf16 v[8:11], v[88:91], v[8:11], v[12:15]
	s_nop 4
	ds_read_b128 v[12:15], v95 offset:58368
	s_waitcnt lgkmcnt(0)
	v_mfma_f32_16x16x32_bf16 v[4:7], v[12:15], v[4:7], v[8:11]
	s_nop 2
	ds_read_b128 v[8:11], v96 offset:58368
	s_waitcnt lgkmcnt(0)
	v_mfma_f32_16x16x32_bf16 v[0:3], v[8:11], v[0:3], v[4:7]
	s_nop 2
	v_mul_f32_e32 v4, v79, v80
	v_mul_f32_e32 v5, v79, v81
	v_max3_f32 v4, v4, s17, v5
	v_mul_f32_e32 v5, v79, v82
	v_mul_f32_e32 v6, v79, v83
	v_max3_f32 v4, v4, v5, v6
	v_mul_f32_e32 v5, v79, v84
	v_mul_f32_e32 v6, v79, v85
	v_max3_f32 v4, v4, v5, v6
	v_mul_f32_e32 v5, v79, v86
	v_mul_f32_e32 v6, v79, v87
	v_max3_f32 v4, v4, v5, v6
	v_mul_f32_e32 v5, v79, v64
	v_mul_f32_e32 v6, v79, v65
	v_max3_f32 v4, v4, v5, v6
	v_mul_f32_e32 v5, v79, v66
	v_mul_f32_e32 v6, v79, v67
	v_max3_f32 v4, v4, v5, v6
	v_mul_f32_e32 v5, v79, v60
	v_mul_f32_e32 v6, v79, v61
	v_max3_f32 v4, v4, v5, v6
	v_mul_f32_e32 v5, v79, v62
	v_mul_f32_e32 v6, v79, v63
	v_max3_f32 v4, v4, v5, v6
	v_mul_f32_e32 v5, v79, v56
	v_mul_f32_e32 v6, v79, v57
	v_max3_f32 v4, v4, v5, v6
	v_mul_f32_e32 v5, v79, v58
	v_mul_f32_e32 v6, v79, v59
	v_max3_f32 v4, v4, v5, v6
	v_mul_f32_e32 v5, v79, v52
	v_mul_f32_e32 v6, v79, v53
	v_max3_f32 v4, v4, v5, v6
	v_mul_f32_e32 v5, v79, v54
	v_mul_f32_e32 v6, v79, v55
	v_max3_f32 v4, v4, v5, v6
	v_mul_f32_e32 v5, v79, v48
	v_mul_f32_e32 v6, v79, v49
	v_max3_f32 v4, v4, v5, v6
	v_mul_f32_e32 v5, v79, v50
	v_mul_f32_e32 v6, v79, v51
	v_max3_f32 v4, v4, v5, v6
	v_mul_f32_e32 v5, v79, v44
	v_mul_f32_e32 v6, v79, v45
	v_max3_f32 v4, v4, v5, v6
	v_mul_f32_e32 v5, v79, v46
	v_mul_f32_e32 v6, v79, v47
	v_max3_f32 v4, v4, v5, v6
	v_mul_f32_e32 v5, v79, v40
	v_mul_f32_e32 v6, v79, v41
	v_max3_f32 v4, v4, v5, v6
	v_mul_f32_e32 v5, v79, v42
	v_mul_f32_e32 v6, v79, v43
	v_max3_f32 v4, v4, v5, v6
	v_mul_f32_e32 v5, v79, v36
	v_mul_f32_e32 v6, v79, v37
	v_max3_f32 v4, v4, v5, v6
	v_mul_f32_e32 v5, v79, v38
	v_mul_f32_e32 v6, v79, v39
	v_max3_f32 v4, v4, v5, v6
	v_mul_f32_e32 v5, v79, v32
	v_mul_f32_e32 v6, v79, v33
	v_max3_f32 v4, v4, v5, v6
	v_mul_f32_e32 v5, v79, v34
	v_mul_f32_e32 v6, v79, v35
	v_max3_f32 v4, v4, v5, v6
	v_mul_f32_e32 v5, v79, v28
	v_mul_f32_e32 v6, v79, v29
	v_max3_f32 v4, v4, v5, v6
	v_mul_f32_e32 v5, v79, v30
	v_mul_f32_e32 v6, v79, v31
	v_max3_f32 v4, v4, v5, v6
	v_mul_f32_e32 v5, v79, v24
	v_mul_f32_e32 v6, v79, v25
	v_max3_f32 v4, v4, v5, v6
	v_mul_f32_e32 v5, v79, v26
	v_mul_f32_e32 v6, v79, v27
	v_max3_f32 v4, v4, v5, v6
	v_mul_f32_e32 v5, v79, v20
	v_mul_f32_e32 v6, v79, v21
	v_max3_f32 v4, v4, v5, v6
	v_mul_f32_e32 v5, v79, v22
	v_mul_f32_e32 v6, v79, v23
	v_max3_f32 v4, v4, v5, v6
	v_mul_f32_e32 v5, v79, v16
	v_mul_f32_e32 v6, v79, v17
	v_max3_f32 v4, v4, v5, v6
	v_mul_f32_e32 v5, v79, v18
	v_mul_f32_e32 v6, v79, v19
	v_max3_f32 v4, v4, v5, v6
	v_mul_f32_e32 v5, v79, v0
	v_mul_f32_e32 v6, v79, v1
	v_max3_f32 v4, v4, v5, v6
	v_mul_f32_e32 v5, v79, v2
	v_mul_f32_e32 v6, v79, v3
	v_max3_f32 v4, v4, v5, v6
	ds_bpermute_b32 v5, v75, v4
	s_waitcnt lgkmcnt(0)
	v_max_f32_e32 v5, v5, v5
	v_max_f32_e32 v4, v4, v5
	ds_bpermute_b32 v5, v78, v4
	s_waitcnt lgkmcnt(0)
	v_max_f32_e32 v5, v5, v5
	v_max_f32_e32 v111, v4, v5
	v_fma_f32 v7, v79, v82, -v111
	v_mul_f32_e32 v7, 0x3fb8aa3b, v7
	v_exp_f32_e32 v8, v7
	v_fma_f32 v7, v79, v83, -v111
	v_fma_f32 v4, v79, v80, -v111
	v_mul_f32_e32 v7, 0x3fb8aa3b, v7
	v_mul_f32_e32 v4, 0x3fb8aa3b, v4
	v_fma_f32 v5, v79, v81, -v111
	v_exp_f32_e32 v9, v7
	v_fma_f32 v7, v79, v84, -v111
	v_exp_f32_e32 v4, v4
	v_mul_f32_e32 v5, 0x3fb8aa3b, v5
	v_mul_f32_e32 v7, 0x3fb8aa3b, v7
	v_exp_f32_e32 v5, v5
	v_exp_f32_e32 v12, v7
	v_fma_f32 v7, v79, v85, -v111
	v_mul_f32_e32 v7, 0x3fb8aa3b, v7
	v_exp_f32_e32 v13, v7
	v_fma_f32 v7, v79, v86, -v111
	v_add_f32_e32 v6, 0, v4
	v_mul_f32_e32 v7, 0x3fb8aa3b, v7
	v_add_f32_e32 v6, v5, v6
	v_exp_f32_e32 v80, v7
	v_fma_f32 v7, v79, v87, -v111
	v_add_f32_e32 v6, v8, v6
	v_mul_f32_e32 v7, 0x3fb8aa3b, v7
	v_add_f32_e32 v6, v9, v6
	v_exp_f32_e32 v81, v7
	v_add_f32_e32 v6, v12, v6
	v_add_f32_e32 v6, v13, v6
	v_add_f32_e32 v6, v80, v6
	v_add_f32_e32 v7, v81, v6
	v_fma_f32 v6, v79, v64, -v111
	v_mul_f32_e32 v6, 0x3fb8aa3b, v6
	v_exp_f32_e32 v6, v6
	v_fma_f32 v11, v79, v66, -v111
	v_mul_f32_e32 v11, 0x3fb8aa3b, v11
	v_exp_f32_e32 v14, v11
	v_fma_f32 v11, v79, v67, -v111
	v_mul_f32_e32 v11, 0x3fb8aa3b, v11
	v_add_f32_e32 v10, v6, v7
	v_fma_f32 v7, v79, v65, -v111
	v_exp_f32_e32 v15, v11
	v_fma_f32 v11, v79, v60, -v111
	v_mul_f32_e32 v7, 0x3fb8aa3b, v7
	v_mul_f32_e32 v11, 0x3fb8aa3b, v11
	v_exp_f32_e32 v7, v7
	v_exp_f32_e32 v60, v11
	v_fma_f32 v11, v79, v61, -v111
	v_mul_f32_e32 v11, 0x3fb8aa3b, v11
	v_exp_f32_e32 v61, v11
	v_fma_f32 v11, v79, v62, -v111
	v_mul_f32_e32 v11, 0x3fb8aa3b, v11
	v_add_f32_e32 v10, v7, v10
	v_exp_f32_e32 v62, v11
	v_fma_f32 v11, v79, v63, -v111
	v_add_f32_e32 v10, v14, v10
	v_mul_f32_e32 v11, 0x3fb8aa3b, v11
	v_add_f32_e32 v10, v15, v10
	v_exp_f32_e32 v63, v11
	v_add_f32_e32 v10, v60, v10
	v_add_f32_e32 v10, v61, v10
	v_add_f32_e32 v10, v62, v10
	v_add_f32_e32 v11, v63, v10
	v_fma_f32 v10, v79, v56, -v111
	v_mul_f32_e32 v10, 0x3fb8aa3b, v10
	v_exp_f32_e32 v10, v10
	v_fma_f32 v52, v79, v52, -v111
	v_mul_f32_e32 v52, 0x3fb8aa3b, v52
	v_fma_f32 v53, v79, v53, -v111
	v_add_f32_e32 v56, v10, v11
	v_fma_f32 v11, v79, v57, -v111
	v_mul_f32_e32 v11, 0x3fb8aa3b, v11
	v_exp_f32_e32 v11, v11
	v_exp_f32_e32 v52, v52
	v_mul_f32_e32 v53, 0x3fb8aa3b, v53
	v_fma_f32 v54, v79, v54, -v111
	v_add_f32_e32 v57, v11, v56
	v_fma_f32 v56, v79, v58, -v111
	v_mul_f32_e32 v56, 0x3fb8aa3b, v56
	v_exp_f32_e32 v56, v56
	v_exp_f32_e32 v53, v53
	v_mul_f32_e32 v54, 0x3fb8aa3b, v54
	v_fma_f32 v55, v79, v55, -v111
	v_add_f32_e32 v58, v56, v57
	v_fma_f32 v57, v79, v59, -v111
	v_mul_f32_e32 v57, 0x3fb8aa3b, v57
	v_exp_f32_e32 v57, v57
	v_exp_f32_e32 v54, v54
	v_mul_f32_e32 v55, 0x3fb8aa3b, v55
	v_fma_f32 v48, v79, v48, -v111
	v_add_f32_e32 v58, v57, v58
	v_exp_f32_e32 v55, v55
	v_mul_f32_e32 v48, 0x3fb8aa3b, v48
	v_fma_f32 v49, v79, v49, -v111
	v_add_f32_e32 v58, v52, v58
	v_exp_f32_e32 v48, v48
	v_mul_f32_e32 v49, 0x3fb8aa3b, v49
	v_fma_f32 v50, v79, v50, -v111
	v_add_f32_e32 v58, v53, v58
	v_exp_f32_e32 v49, v49
	v_mul_f32_e32 v50, 0x3fb8aa3b, v50
	v_fma_f32 v51, v79, v51, -v111
	v_add_f32_e32 v58, v54, v58
	v_exp_f32_e32 v50, v50
	v_mul_f32_e32 v51, 0x3fb8aa3b, v51
	v_add_f32_e32 v58, v55, v58
	v_exp_f32_e32 v51, v51
	v_add_f32_e32 v58, v48, v58
	v_add_f32_e32 v58, v49, v58
	v_fma_f32 v44, v79, v44, -v111
	v_add_f32_e32 v58, v50, v58
	v_mul_f32_e32 v44, 0x3fb8aa3b, v44
	v_add_f32_e32 v59, v51, v58
	v_exp_f32_e32 v58, v44
	v_fma_f32 v45, v79, v45, -v111
	v_mul_f32_e32 v45, 0x3fb8aa3b, v45
	v_fma_f32 v41, v79, v41, -v111
	v_add_f32_e32 v44, v58, v59
	v_exp_f32_e32 v59, v45
	v_fma_f32 v45, v79, v46, -v111
	v_mul_f32_e32 v45, 0x3fb8aa3b, v45
	v_exp_f32_e32 v64, v45
	v_fma_f32 v45, v79, v47, -v111
	v_mul_f32_e32 v45, 0x3fb8aa3b, v45
	v_fma_f32 v40, v79, v40, -v111
	v_mul_f32_e32 v41, 0x3fb8aa3b, v41
	v_exp_f32_e32 v65, v45
	v_mul_f32_e32 v40, 0x3fb8aa3b, v40
	v_exp_f32_e32 v67, v41
	v_fma_f32 v41, v79, v42, -v111
	v_exp_f32_e32 v66, v40
	v_mul_f32_e32 v41, 0x3fb8aa3b, v41
	v_add_f32_e32 v44, v59, v44
	v_exp_f32_e32 v82, v41
	v_fma_f32 v41, v79, v43, -v111
	v_fma_f32 v37, v79, v37, -v111
	v_add_f32_e32 v44, v64, v44
	v_mul_f32_e32 v41, 0x3fb8aa3b, v41
	v_fma_f32 v36, v79, v36, -v111
	v_mul_f32_e32 v37, 0x3fb8aa3b, v37
	v_add_f32_e32 v44, v65, v44
	v_exp_f32_e32 v83, v41
	v_mul_f32_e32 v36, 0x3fb8aa3b, v36
	v_exp_f32_e32 v85, v37
	v_fma_f32 v37, v79, v38, -v111
	v_add_f32_e32 v40, v66, v44
	v_exp_f32_e32 v84, v36
	v_mul_f32_e32 v37, 0x3fb8aa3b, v37
	v_add_f32_e32 v40, v67, v40
	v_exp_f32_e32 v86, v37
	v_fma_f32 v37, v79, v39, -v111
	v_fma_f32 v33, v79, v33, -v111
	v_add_f32_e32 v40, v82, v40
	v_mul_f32_e32 v37, 0x3fb8aa3b, v37
	v_fma_f32 v32, v79, v32, -v111
	v_mul_f32_e32 v33, 0x3fb8aa3b, v33
	v_add_f32_e32 v40, v83, v40
	v_exp_f32_e32 v87, v37
	v_mul_f32_e32 v32, 0x3fb8aa3b, v32
	v_exp_f32_e32 v89, v33
	v_fma_f32 v33, v79, v34, -v111
	v_add_f32_e32 v36, v84, v40
	v_exp_f32_e32 v88, v32
	v_mul_f32_e32 v33, 0x3fb8aa3b, v33
	v_add_f32_e32 v36, v85, v36
	v_exp_f32_e32 v90, v33
	v_fma_f32 v33, v79, v35, -v111
	v_fma_f32 v29, v79, v29, -v111
	v_add_f32_e32 v36, v86, v36
	v_mul_f32_e32 v33, 0x3fb8aa3b, v33
	v_fma_f32 v28, v79, v28, -v111
	v_mul_f32_e32 v29, 0x3fb8aa3b, v29
	v_add_f32_e32 v36, v87, v36
	v_exp_f32_e32 v91, v33
	v_mul_f32_e32 v28, 0x3fb8aa3b, v28
	v_exp_f32_e32 v93, v29
	v_fma_f32 v29, v79, v30, -v111
	v_add_f32_e32 v32, v88, v36
	v_exp_f32_e32 v92, v28
	v_mul_f32_e32 v29, 0x3fb8aa3b, v29
	v_add_f32_e32 v32, v89, v32
	v_exp_f32_e32 v94, v29
	v_fma_f32 v29, v79, v31, -v111
	v_fma_f32 v25, v79, v25, -v111
	v_add_f32_e32 v32, v90, v32
	v_mul_f32_e32 v29, 0x3fb8aa3b, v29
	v_fma_f32 v24, v79, v24, -v111
	v_mul_f32_e32 v25, 0x3fb8aa3b, v25
	v_add_f32_e32 v32, v91, v32
	v_exp_f32_e32 v95, v29
	v_mul_f32_e32 v24, 0x3fb8aa3b, v24
	v_exp_f32_e32 v97, v25
	v_fma_f32 v25, v79, v26, -v111
	v_add_f32_e32 v28, v92, v32
	v_exp_f32_e32 v96, v24
	v_mul_f32_e32 v25, 0x3fb8aa3b, v25
	v_add_f32_e32 v28, v93, v28
	v_exp_f32_e32 v98, v25
	v_fma_f32 v25, v79, v27, -v111
	v_fma_f32 v21, v79, v21, -v111
	v_add_f32_e32 v28, v94, v28
	v_mul_f32_e32 v25, 0x3fb8aa3b, v25
	v_fma_f32 v20, v79, v20, -v111
	v_mul_f32_e32 v21, 0x3fb8aa3b, v21
	v_add_f32_e32 v28, v95, v28
	v_exp_f32_e32 v99, v25
	v_mul_f32_e32 v20, 0x3fb8aa3b, v20
	v_exp_f32_e32 v101, v21
	v_fma_f32 v21, v79, v22, -v111
	v_add_f32_e32 v24, v96, v28
	v_exp_f32_e32 v100, v20
	v_mul_f32_e32 v21, 0x3fb8aa3b, v21
	v_add_f32_e32 v24, v97, v24
	v_exp_f32_e32 v102, v21
	v_fma_f32 v21, v79, v23, -v111
	v_fma_f32 v17, v79, v17, -v111
	v_add_f32_e32 v24, v98, v24
	v_mul_f32_e32 v21, 0x3fb8aa3b, v21
	v_fma_f32 v16, v79, v16, -v111
	v_mul_f32_e32 v17, 0x3fb8aa3b, v17
	v_add_f32_e32 v24, v99, v24
	v_exp_f32_e32 v103, v21
	v_mul_f32_e32 v16, 0x3fb8aa3b, v16
	v_exp_f32_e32 v105, v17
	v_fma_f32 v17, v79, v18, -v111
	v_add_f32_e32 v20, v100, v24
	v_exp_f32_e32 v104, v16
	v_mul_f32_e32 v17, 0x3fb8aa3b, v17
	v_add_f32_e32 v20, v101, v20
	v_exp_f32_e32 v106, v17
	v_fma_f32 v17, v79, v19, -v111
	v_fma_f32 v1, v79, v1, -v111
	v_add_f32_e32 v20, v102, v20
	v_mul_f32_e32 v17, 0x3fb8aa3b, v17
	v_fma_f32 v0, v79, v0, -v111
	v_mul_f32_e32 v1, 0x3fb8aa3b, v1
	v_add_f32_e32 v20, v103, v20
	v_exp_f32_e32 v107, v17
	v_mul_f32_e32 v0, 0x3fb8aa3b, v0
	v_exp_f32_e32 v109, v1
	v_fma_f32 v1, v79, v2, -v111
	v_add_f32_e32 v16, v104, v20
	v_exp_f32_e32 v108, v0
	v_mul_f32_e32 v1, 0x3fb8aa3b, v1
	v_add_f32_e32 v16, v105, v16
	v_exp_f32_e32 v110, v1
	v_fma_f32 v1, v79, v3, -v111
	v_add_f32_e32 v16, v106, v16
	v_mul_f32_e32 v1, 0x3fb8aa3b, v1
	v_add_f32_e32 v16, v107, v16
	v_exp_f32_e32 v111, v1
	v_add_f32_e32 v0, v108, v16
	v_add_f32_e32 v0, v109, v0
	v_add_f32_e32 v0, v110, v0
	v_add_f32_e32 v0, v111, v0
	ds_bpermute_b32 v1, v75, v0
	v_lshl_add_u32 v75, v71, 9, s3
	s_addc_u32 s3, s8, 0
	s_add_i32 s10, s10, s90
	s_add_i32 s9, s9, s30
	s_waitcnt lgkmcnt(0)
	v_add_f32_e32 v0, v0, v1
	ds_bpermute_b32 v1, v78, v0
	s_cmpk_gt_i32 s10, 0x1ff
	s_waitcnt lgkmcnt(0)
	v_add_f32_e32 v0, v0, v1
	v_div_scale_f32 v1, s[4:5], v0, v0, 1.0
	v_rcp_f32_e32 v2, v1
	s_nop 0
	v_fma_f32 v3, -v1, v2, 1.0
	v_fmac_f32_e32 v2, v3, v2
	v_div_scale_f32 v3, vcc, 1.0, v0, 1.0
	v_mul_f32_e32 v16, v3, v2
	v_fma_f32 v17, -v1, v16, v3
	v_fmac_f32_e32 v16, v17, v2
	v_fma_f32 v1, -v1, v16, v3
	v_div_fmas_f32 v1, v1, v2, v16
	v_div_fixup_f32 v78, v1, v0, 1.0
	v_pk_mul_f32 v[2:3], v[8:9], v[78:79] op_sel_hi:[1,0]
	v_pk_mul_f32 v[0:1], v[4:5], v[78:79] op_sel_hi:[1,0]
	v_pk_mul_f32 v[4:5], v[80:81], v[78:79] op_sel_hi:[1,0]
	v_pk_mul_f32 v[8:9], v[12:13], v[78:79] op_sel_hi:[1,0]
	v_cvt_pk_bf16_f32 v0, v0, v1
	v_cvt_pk_bf16_f32 v1, v2, v3
	v_cvt_pk_bf16_f32 v3, v4, v5
	v_add_u32_e32 v4, v75, v77
	v_cvt_pk_bf16_f32 v2, v8, v9
	ds_read_b128 v[16:19], v4
	ds_read_b128 v[20:23], v4 offset:8192
	ds_read_b128 v[24:27], v4 offset:16384
	ds_read_b128 v[28:31], v4 offset:24576
	ds_read_b128 v[32:35], v4 offset:32768
	ds_read_b128 v[36:39], v4 offset:40960
	ds_read_b128 v[40:43], v4 offset:49152
	ds_read_b128 v[44:47], v4 offset:57344
	v_pk_mul_f32 v[8:9], v[14:15], v[78:79] op_sel_hi:[1,0]
	v_pk_mul_f32 v[4:5], v[6:7], v[78:79] op_sel_hi:[1,0]
	v_pk_mul_f32 v[12:13], v[62:63], v[78:79] op_sel_hi:[1,0]
	v_pk_mul_f32 v[6:7], v[60:61], v[78:79] op_sel_hi:[1,0]
	v_cvt_pk_bf16_f32 v4, v4, v5
	v_cvt_pk_bf16_f32 v5, v8, v9
	v_add_u32_e32 v8, v75, v76
	v_cvt_pk_bf16_f32 v6, v6, v7
	v_cvt_pk_bf16_f32 v7, v12, v13
	ds_read_b128 v[12:15], v8
	s_waitcnt lgkmcnt(8)
	v_mfma_f32_16x16x32_bf16 v[16:19], v[0:3], v[16:19], 0
	s_waitcnt lgkmcnt(0)
	v_mfma_f32_16x16x32_bf16 v[12:15], v[4:7], v[12:15], v[16:19]
	v_mfma_f32_16x16x32_bf16 v[20:23], v[0:3], v[20:23], 0
	s_nop 4
	ds_read_b128 v[16:19], v8 offset:8192
	s_waitcnt lgkmcnt(0)
	v_mfma_f32_16x16x32_bf16 v[16:19], v[4:7], v[16:19], v[20:23]
	s_nop 2
	ds_read_b128 v[20:23], v8 offset:16384
	v_mfma_f32_16x16x32_bf16 v[24:27], v[0:3], v[24:27], 0
	s_waitcnt lgkmcnt(0)
	v_mfma_f32_16x16x32_bf16 v[20:23], v[4:7], v[20:23], v[24:27]
	v_mfma_f32_16x16x32_bf16 v[28:31], v[0:3], v[28:31], 0
	s_nop 4
	ds_read_b128 v[24:27], v8 offset:24576
	s_waitcnt lgkmcnt(0)
	v_mfma_f32_16x16x32_bf16 v[24:27], v[4:7], v[24:27], v[28:31]
	s_nop 2
	ds_read_b128 v[28:31], v8 offset:32768
	v_mfma_f32_16x16x32_bf16 v[32:35], v[0:3], v[32:35], 0
	s_waitcnt lgkmcnt(0)
	v_mfma_f32_16x16x32_bf16 v[28:31], v[4:7], v[28:31], v[32:35]
	v_mfma_f32_16x16x32_bf16 v[36:39], v[0:3], v[36:39], 0
	s_nop 4
	ds_read_b128 v[32:35], v8 offset:40960
	s_waitcnt lgkmcnt(0)
	v_mfma_f32_16x16x32_bf16 v[32:35], v[4:7], v[32:35], v[36:39]
	s_nop 2
	ds_read_b128 v[36:39], v8 offset:49152
	v_mfma_f32_16x16x32_bf16 v[40:43], v[0:3], v[40:43], 0
	s_waitcnt lgkmcnt(0)
	v_mfma_f32_16x16x32_bf16 v[36:39], v[4:7], v[36:39], v[40:43]
	v_mfma_f32_16x16x32_bf16 v[0:3], v[0:3], v[44:47], 0
	s_nop 4
	ds_read_b128 v[40:43], v8 offset:57344
	v_pk_mul_f32 v[8:9], v[54:55], v[78:79] op_sel_hi:[1,0]
	s_waitcnt lgkmcnt(0)
	v_mfma_f32_16x16x32_bf16 v[0:3], v[4:7], v[40:43], v[0:3]
	v_mul_f32_e64 v6, v56, v78
	v_mul_f32_e64 v7, v57, v78
	v_pk_mul_f32 v[4:5], v[10:11], v[78:79] op_sel_hi:[1,0]
	v_pk_mul_f32 v[10:11], v[52:53], v[78:79] op_sel_hi:[1,0]
	v_add_u32_e32 v40, v75, v74
	v_cvt_pk_bf16_f32 v4, v4, v5
	v_cvt_pk_bf16_f32 v5, v6, v7
	v_cvt_pk_bf16_f32 v6, v10, v11
	v_cvt_pk_bf16_f32 v7, v8, v9
	ds_read_b128 v[8:11], v40
	s_waitcnt lgkmcnt(0)
	v_mfma_f32_16x16x32_bf16 v[8:11], v[4:7], v[8:11], v[12:15]
	s_nop 2
	ds_read_b128 v[12:15], v40 offset:8192
	s_waitcnt lgkmcnt(0)
	v_mfma_f32_16x16x32_bf16 v[12:15], v[4:7], v[12:15], v[16:19]
	s_nop 2
	ds_read_b128 v[16:19], v40 offset:16384
	s_waitcnt lgkmcnt(0)
	v_mfma_f32_16x16x32_bf16 v[16:19], v[4:7], v[16:19], v[20:23]
	s_nop 2
	ds_read_b128 v[20:23], v40 offset:24576
	s_waitcnt lgkmcnt(0)
	v_mfma_f32_16x16x32_bf16 v[20:23], v[4:7], v[20:23], v[24:27]
	s_nop 2
	ds_read_b128 v[24:27], v40 offset:32768
	s_waitcnt lgkmcnt(0)
	v_mfma_f32_16x16x32_bf16 v[24:27], v[4:7], v[24:27], v[28:31]
	s_nop 2
	ds_read_b128 v[28:31], v40 offset:40960
	s_waitcnt lgkmcnt(0)
	v_mfma_f32_16x16x32_bf16 v[28:31], v[4:7], v[28:31], v[32:35]
	s_nop 2
	ds_read_b128 v[32:35], v40 offset:49152
	s_waitcnt lgkmcnt(0)
	v_mfma_f32_16x16x32_bf16 v[32:35], v[4:7], v[32:35], v[36:39]
	s_nop 2
	ds_read_b128 v[36:39], v40 offset:57344
	v_add_u32_e32 v40, v75, v73
	s_waitcnt lgkmcnt(0)
	v_mfma_f32_16x16x32_bf16 v[0:3], v[4:7], v[36:39], v[0:3]
	v_mul_f32_e64 v6, v50, v78
	v_mul_f32_e64 v7, v51, v78
	v_pk_mul_f32 v[4:5], v[48:49], v[78:79] op_sel_hi:[1,0]
	v_pk_mul_f32 v[36:37], v[64:65], v[78:79] op_sel_hi:[1,0]
	v_pk_mul_f32 v[38:39], v[58:59], v[78:79] op_sel_hi:[1,0]
	v_cvt_pk_bf16_f32 v4, v4, v5
	v_cvt_pk_bf16_f32 v5, v6, v7
	v_cvt_pk_bf16_f32 v6, v38, v39
	v_cvt_pk_bf16_f32 v7, v36, v37
	ds_read_b128 v[36:39], v40
	s_waitcnt lgkmcnt(0)
	v_mfma_f32_16x16x32_bf16 v[8:11], v[4:7], v[36:39], v[8:11]
	ds_read_b128 v[36:39], v40 offset:8192
	s_waitcnt lgkmcnt(0)
	v_mfma_f32_16x16x32_bf16 v[12:15], v[4:7], v[36:39], v[12:15]
	ds_read_b128 v[36:39], v40 offset:16384
	s_waitcnt lgkmcnt(0)
	v_mfma_f32_16x16x32_bf16 v[16:19], v[4:7], v[36:39], v[16:19]
	ds_read_b128 v[36:39], v40 offset:24576
	s_waitcnt lgkmcnt(0)
	v_mfma_f32_16x16x32_bf16 v[20:23], v[4:7], v[36:39], v[20:23]
	ds_read_b128 v[36:39], v40 offset:32768
	s_waitcnt lgkmcnt(0)
	v_mfma_f32_16x16x32_bf16 v[24:27], v[4:7], v[36:39], v[24:27]
	ds_read_b128 v[36:39], v40 offset:40960
	s_waitcnt lgkmcnt(0)
	v_mfma_f32_16x16x32_bf16 v[28:31], v[4:7], v[36:39], v[28:31]
	ds_read_b128 v[36:39], v40 offset:49152
	s_waitcnt lgkmcnt(0)
	v_mfma_f32_16x16x32_bf16 v[32:35], v[4:7], v[36:39], v[32:35]
	ds_read_b128 v[36:39], v40 offset:57344
	s_waitcnt lgkmcnt(0)
	v_mfma_f32_16x16x32_bf16 v[0:3], v[4:7], v[36:39], v[0:3]
	v_mul_f32_e64 v6, v82, v78
	v_mul_f32_e64 v7, v83, v78
	v_pk_mul_f32 v[4:5], v[66:67], v[78:79] op_sel_hi:[1,0]
	v_pk_mul_f32 v[36:37], v[86:87], v[78:79] op_sel_hi:[1,0]
	v_cvt_pk_bf16_f32 v4, v4, v5
	v_cvt_pk_bf16_f32 v5, v6, v7
	v_cvt_pk_bf16_f32 v7, v36, v37
	v_bitop3_b32 v36, v70, v71, 16 bitop3:0x36
	v_pk_mul_f32 v[38:39], v[84:85], v[78:79] op_sel_hi:[1,0]
	v_lshl_add_u32 v40, v36, 4, v75
	v_cvt_pk_bf16_f32 v6, v38, v39
	ds_read_b128 v[36:39], v40
	s_waitcnt lgkmcnt(0)
	v_mfma_f32_16x16x32_bf16 v[8:11], v[4:7], v[36:39], v[8:11]
	ds_read_b128 v[36:39], v40 offset:8192
	s_waitcnt lgkmcnt(0)
	v_mfma_f32_16x16x32_bf16 v[12:15], v[4:7], v[36:39], v[12:15]
	ds_read_b128 v[36:39], v40 offset:16384
	s_waitcnt lgkmcnt(0)
	v_mfma_f32_16x16x32_bf16 v[16:19], v[4:7], v[36:39], v[16:19]
	ds_read_b128 v[36:39], v40 offset:24576
	s_waitcnt lgkmcnt(0)
	v_mfma_f32_16x16x32_bf16 v[20:23], v[4:7], v[36:39], v[20:23]
	ds_read_b128 v[36:39], v40 offset:32768
	s_waitcnt lgkmcnt(0)
	v_mfma_f32_16x16x32_bf16 v[24:27], v[4:7], v[36:39], v[24:27]
	ds_read_b128 v[36:39], v40 offset:40960
	s_waitcnt lgkmcnt(0)
	v_mfma_f32_16x16x32_bf16 v[28:31], v[4:7], v[36:39], v[28:31]
	ds_read_b128 v[36:39], v40 offset:49152
	s_waitcnt lgkmcnt(0)
	v_mfma_f32_16x16x32_bf16 v[32:35], v[4:7], v[36:39], v[32:35]
	ds_read_b128 v[36:39], v40 offset:57344
	s_waitcnt lgkmcnt(0)
	v_mfma_f32_16x16x32_bf16 v[0:3], v[4:7], v[36:39], v[0:3]
	v_mul_f32_e64 v6, v90, v78
	v_mul_f32_e64 v7, v91, v78
	v_pk_mul_f32 v[4:5], v[88:89], v[78:79] op_sel_hi:[1,0]
	v_pk_mul_f32 v[36:37], v[94:95], v[78:79] op_sel_hi:[1,0]
	v_cvt_pk_bf16_f32 v4, v4, v5
	v_cvt_pk_bf16_f32 v5, v6, v7
	v_cvt_pk_bf16_f32 v7, v36, v37
	v_bitop3_b32 v36, v70, v71, 20 bitop3:0x36
	v_pk_mul_f32 v[38:39], v[92:93], v[78:79] op_sel_hi:[1,0]
	v_lshl_add_u32 v40, v36, 4, v75
	v_cvt_pk_bf16_f32 v6, v38, v39
	ds_read_b128 v[36:39], v40
	s_waitcnt lgkmcnt(0)
	v_mfma_f32_16x16x32_bf16 v[8:11], v[4:7], v[36:39], v[8:11]
	ds_read_b128 v[36:39], v40 offset:8192
	s_waitcnt lgkmcnt(0)
	v_mfma_f32_16x16x32_bf16 v[12:15], v[4:7], v[36:39], v[12:15]
	ds_read_b128 v[36:39], v40 offset:16384
	s_waitcnt lgkmcnt(0)
	v_mfma_f32_16x16x32_bf16 v[16:19], v[4:7], v[36:39], v[16:19]
	ds_read_b128 v[36:39], v40 offset:24576
	s_waitcnt lgkmcnt(0)
	v_mfma_f32_16x16x32_bf16 v[20:23], v[4:7], v[36:39], v[20:23]
	ds_read_b128 v[36:39], v40 offset:32768
	s_waitcnt lgkmcnt(0)
	v_mfma_f32_16x16x32_bf16 v[24:27], v[4:7], v[36:39], v[24:27]
	ds_read_b128 v[36:39], v40 offset:40960
	s_waitcnt lgkmcnt(0)
	v_mfma_f32_16x16x32_bf16 v[28:31], v[4:7], v[36:39], v[28:31]
	ds_read_b128 v[36:39], v40 offset:49152
	s_waitcnt lgkmcnt(0)
	v_mfma_f32_16x16x32_bf16 v[32:35], v[4:7], v[36:39], v[32:35]
	ds_read_b128 v[36:39], v40 offset:57344
	s_waitcnt lgkmcnt(0)
	v_mfma_f32_16x16x32_bf16 v[0:3], v[4:7], v[36:39], v[0:3]
	v_mul_f32_e64 v6, v98, v78
	v_mul_f32_e64 v7, v99, v78
	v_pk_mul_f32 v[4:5], v[96:97], v[78:79] op_sel_hi:[1,0]
	v_pk_mul_f32 v[36:37], v[102:103], v[78:79] op_sel_hi:[1,0]
	v_cvt_pk_bf16_f32 v4, v4, v5
	v_cvt_pk_bf16_f32 v5, v6, v7
	v_cvt_pk_bf16_f32 v7, v36, v37
	v_bitop3_b32 v36, v70, v71, 24 bitop3:0x36
	v_pk_mul_f32 v[38:39], v[100:101], v[78:79] op_sel_hi:[1,0]
	v_lshl_add_u32 v48, v36, 4, v75
	v_cvt_pk_bf16_f32 v6, v38, v39
	ds_read_b128 v[36:39], v48
	s_waitcnt lgkmcnt(0)
	v_mfma_f32_16x16x32_bf16 v[8:11], v[4:7], v[36:39], v[8:11]
	ds_read_b128 v[36:39], v48 offset:8192
	s_waitcnt lgkmcnt(0)
	v_mfma_f32_16x16x32_bf16 v[12:15], v[4:7], v[36:39], v[12:15]
	ds_read_b128 v[36:39], v48 offset:16384
	s_waitcnt lgkmcnt(0)
	v_mfma_f32_16x16x32_bf16 v[16:19], v[4:7], v[36:39], v[16:19]
	ds_read_b128 v[36:39], v48 offset:24576
	s_waitcnt lgkmcnt(0)
	v_mfma_f32_16x16x32_bf16 v[36:39], v[4:7], v[36:39], v[20:23]
	s_nop 2
	ds_read_b128 v[20:23], v48 offset:32768
	s_waitcnt lgkmcnt(0)
	v_mfma_f32_16x16x32_bf16 v[40:43], v[4:7], v[20:23], v[24:27]
	ds_read_b128 v[20:23], v48 offset:40960
	s_waitcnt lgkmcnt(0)
	v_mfma_f32_16x16x32_bf16 v[44:47], v[4:7], v[20:23], v[28:31]
	ds_read_b128 v[20:23], v48 offset:49152
	s_waitcnt lgkmcnt(0)
	v_mfma_f32_16x16x32_bf16 v[32:35], v[4:7], v[20:23], v[32:35]
	ds_read_b128 v[20:23], v48 offset:57344
	s_waitcnt lgkmcnt(0)
	v_mfma_f32_16x16x32_bf16 v[0:3], v[4:7], v[20:23], v[0:3]
	v_mul_f32_e64 v4, v106, v78
	v_mul_f32_e64 v5, v107, v78
	v_pk_mul_f32 v[6:7], v[104:105], v[78:79] op_sel_hi:[1,0]
	v_cvt_pk_bf16_f32 v49, v4, v5
	v_bitop3_b32 v4, v70, v71, 28 bitop3:0x36
	v_pk_mul_f32 v[20:21], v[110:111], v[78:79] op_sel_hi:[1,0]
	v_pk_mul_f32 v[22:23], v[108:109], v[78:79] op_sel_hi:[1,0]
	v_lshl_add_u32 v52, v4, 4, v75
	v_cvt_pk_bf16_f32 v48, v6, v7
	v_cvt_pk_bf16_f32 v50, v22, v23
	v_cvt_pk_bf16_f32 v51, v20, v21
	ds_read_b128 v[4:7], v52
	s_waitcnt lgkmcnt(0)
	v_mfma_f32_16x16x32_bf16 v[28:31], v[48:51], v[4:7], v[8:11]
	ds_read_b128 v[4:7], v52 offset:8192
	s_waitcnt lgkmcnt(0)
	v_mfma_f32_16x16x32_bf16 v[24:27], v[48:51], v[4:7], v[12:15]
	ds_read_b128 v[4:7], v52 offset:16384
	s_waitcnt lgkmcnt(0)
	v_mfma_f32_16x16x32_bf16 v[20:23], v[48:51], v[4:7], v[16:19]
	ds_read_b128 v[4:7], v52 offset:24576
	s_waitcnt lgkmcnt(0)
	v_mfma_f32_16x16x32_bf16 v[16:19], v[48:51], v[4:7], v[36:39]
	ds_read_b128 v[4:7], v52 offset:32768
	s_waitcnt lgkmcnt(0)
	v_mfma_f32_16x16x32_bf16 v[12:15], v[48:51], v[4:7], v[40:43]
	ds_read_b128 v[4:7], v52 offset:40960
	s_nop 1
	v_pk_mul_f32 v[42:43], v[24:25], v[24:25]
	s_waitcnt lgkmcnt(0)
	v_mfma_f32_16x16x32_bf16 v[8:11], v[48:51], v[4:7], v[44:47]
	ds_read_b128 v[4:7], v52 offset:49152
	v_pk_fma_f32 v[42:43], v[28:29], v[28:29], v[42:43]
	s_nop 0
	v_mov_b32_e32 v44, v13
	s_waitcnt lgkmcnt(0)
	v_mfma_f32_16x16x32_bf16 v[4:7], v[48:51], v[4:7], v[32:35]
	s_nop 1
	v_mov_b32_e32 v45, v9
	ds_read_b128 v[32:35], v52 offset:57344
	v_pk_mul_f32 v[44:45], v[44:45], v[44:45]
	s_waitcnt lgkmcnt(0)
	v_mfma_f32_16x16x32_bf16 v[0:3], v[48:51], v[32:35], v[0:3]
	v_xor_b32_e32 v32, 1, v225
	v_cmp_lt_i32_e32 vcc, v32, v69
	v_mov_b32_e32 v33, v16
	v_mov_b32_e32 v46, v5
	v_cndmask_b32_e32 v32, v225, v32, vcc
	v_lshlrev_b32_e32 v52, 2, v32
	v_xor_b32_e32 v32, 2, v225
	v_cmp_lt_i32_e32 vcc, v32, v69
	v_mov_b32_e32 v47, v1
	v_pk_mul_f32 v[46:47], v[46:47], v[46:47]
	v_cndmask_b32_e32 v32, v225, v32, vcc
	v_lshlrev_b32_e32 v53, 2, v32
	v_xor_b32_e32 v32, 4, v225
	v_cmp_lt_i32_e32 vcc, v32, v69
	s_nop 1
	v_cndmask_b32_e32 v32, v225, v32, vcc
	v_lshlrev_b32_e32 v54, 2, v32
	v_xor_b32_e32 v32, 8, v225
	v_cmp_lt_i32_e32 vcc, v32, v69
	v_ashrrev_i32_e32 v69, 31, v68
	s_nop 0
	v_cndmask_b32_e32 v32, v225, v32, vcc
	v_lshlrev_b32_e32 v55, 2, v32
	v_mov_b32_e32 v32, v20
	v_pk_mul_f32 v[34:35], v[32:33], v[32:33]
	v_mov_b32_e32 v32, v12
	v_mov_b32_e32 v33, v8
	v_pk_mul_f32 v[36:37], v[32:33], v[32:33]
	v_mov_b32_e32 v32, v4
	v_mov_b32_e32 v33, v0
	v_pk_mul_f32 v[38:39], v[32:33], v[32:33]
	v_mov_b32_e32 v32, v21
	v_mov_b32_e32 v33, v17
	v_pk_mul_f32 v[40:41], v[32:33], v[32:33]
	v_mov_b32_e32 v49, v34
	v_mov_b32_e32 v48, v40
	v_pk_add_f32 v[42:43], v[42:43], v[48:49] op_sel:[1,0] op_sel_hi:[0,1]
	v_mov_b32_e32 v34, v41
	v_pk_add_f32 v[34:35], v[42:43], v[34:35]
	v_mov_b32_e32 v40, v44
	v_mov_b32_e32 v41, v36
	v_pk_add_f32 v[34:35], v[34:35], v[40:41]
	v_mov_b32_e32 v36, v45
	v_pk_add_f32 v[34:35], v[34:35], v[36:37]
	v_mov_b32_e32 v36, v46
	v_mov_b32_e32 v37, v38
	v_pk_add_f32 v[34:35], v[34:35], v[36:37]
	v_mov_b32_e32 v38, v47
	v_pk_add_f32 v[34:35], v[34:35], v[38:39]
	ds_bpermute_b32 v37, v52, v35
	ds_bpermute_b32 v36, v52, v34
	v_mov_b32_e32 v44, v23
	v_mov_b32_e32 v45, v19
	v_pk_mul_f32 v[32:33], v[26:27], v[26:27]
	v_pk_mul_f32 v[44:45], v[44:45], v[44:45]
	s_waitcnt lgkmcnt(0)
	v_pk_add_f32 v[34:35], v[34:35], v[36:37]
	ds_bpermute_b32 v37, v53, v35
	ds_bpermute_b32 v36, v53, v34
	v_pk_fma_f32 v[32:33], v[30:31], v[30:31], v[32:33]
	v_mov_b32_e32 v40, v14
	v_mov_b32_e32 v41, v10
	v_mov_b32_e32 v46, v15
	s_waitcnt lgkmcnt(0)
	v_pk_add_f32 v[34:35], v[34:35], v[36:37]
	ds_bpermute_b32 v37, v54, v35
	ds_bpermute_b32 v36, v54, v34
	v_mov_b32_e32 v47, v11
	v_mov_b32_e32 v50, v44
	v_pk_mul_f32 v[40:41], v[40:41], v[40:41]
	v_pk_mul_f32 v[46:47], v[46:47], v[46:47]
	s_waitcnt lgkmcnt(0)
	v_pk_add_f32 v[34:35], v[34:35], v[36:37]
	ds_bpermute_b32 v37, v55, v35
	ds_bpermute_b32 v36, v55, v34
	v_mov_b32_e32 v42, v6
	v_mov_b32_e32 v43, v2
	v_mov_b32_e32 v48, v7
	v_mov_b32_e32 v49, v3
	s_waitcnt lgkmcnt(0)
	v_pk_add_f32 v[34:35], v[34:35], v[36:37]
	v_mov_b64_e32 v[36:37], s[20:21]
	v_pk_fma_f32 v[38:39], v[34:35], s[36:37], v[36:37] op_sel_hi:[1,0,0]
	v_pk_mul_f32 v[42:43], v[42:43], v[42:43]
	v_mul_f32_e32 v34, 0x4b800000, v39
	v_cmp_gt_f32_e64 s[4:5], s33, v39
	v_cmp_gt_f32_e32 vcc, s33, v38
	v_pk_mul_f32 v[48:49], v[48:49], v[48:49]
	v_cndmask_b32_e64 v34, v39, v34, s[4:5]
	v_rsq_f32_e32 v34, v34
	v_mov_b32_e32 v39, v18
	v_mul_f32_e32 v35, 0x45800000, v34
	v_cndmask_b32_e64 v34, v34, v35, s[4:5]
	v_mul_f32_e32 v35, 0x4b800000, v38
	v_cndmask_b32_e32 v35, v38, v35, vcc
	v_rsq_f32_e32 v35, v35
	v_mul_f32_e32 v28, v28, v34
	v_mul_f32_e32 v24, v24, v34
	v_mul_f32_e32 v20, v20, v34
	v_mul_f32_e32 v38, 0x45800000, v35
	v_cndmask_b32_e32 v35, v35, v38, vcc
	v_mov_b32_e32 v38, v22
	v_pk_mul_f32 v[38:39], v[38:39], v[38:39]
	v_mul_f32_e32 v16, v16, v34
	v_mov_b32_e32 v51, v38
	v_pk_add_f32 v[32:33], v[32:33], v[50:51] op_sel:[1,0] op_sel_hi:[0,1]
	v_mov_b32_e32 v38, v45
	v_pk_add_f32 v[32:33], v[32:33], v[38:39]
	v_mov_b32_e32 v38, v46
	v_mov_b32_e32 v39, v40
	v_pk_add_f32 v[32:33], v[32:33], v[38:39]
	v_mov_b32_e32 v40, v47
	v_pk_add_f32 v[32:33], v[32:33], v[40:41]
	v_mov_b32_e32 v38, v48
	v_mov_b32_e32 v39, v42
	v_pk_add_f32 v[32:33], v[32:33], v[38:39]
	v_mov_b32_e32 v42, v49
	v_pk_add_f32 v[32:33], v[32:33], v[42:43]
	ds_bpermute_b32 v39, v52, v33
	ds_bpermute_b32 v38, v52, v32
	v_mul_f32_e32 v12, v12, v34
	v_mul_f32_e32 v8, v8, v34
	v_mul_f32_e32 v4, v4, v34
	v_mul_f32_e32 v0, v0, v34
	s_waitcnt lgkmcnt(0)
	v_pk_add_f32 v[32:33], v[32:33], v[38:39]
	ds_bpermute_b32 v39, v53, v33
	ds_bpermute_b32 v38, v53, v32
	s_waitcnt lgkmcnt(0)
	v_pk_add_f32 v[32:33], v[32:33], v[38:39]
	ds_bpermute_b32 v39, v54, v33
	ds_bpermute_b32 v38, v54, v32
	s_waitcnt lgkmcnt(0)
	v_pk_add_f32 v[32:33], v[32:33], v[38:39]
	ds_bpermute_b32 v39, v55, v33
	ds_bpermute_b32 v38, v55, v32
	s_waitcnt lgkmcnt(0)
	v_pk_add_f32 v[32:33], v[32:33], v[38:39]
	v_lshlrev_b32_e32 v38, 2, v71
	global_load_dword v112, v38, s[2:3]
	global_load_dword v113, v38, s[2:3] offset:64
	global_load_dword v114, v38, s[2:3] offset:128
	global_load_dword v115, v38, s[2:3] offset:192
	global_load_dword v116, v38, s[2:3] offset:256
	global_load_dword v117, v38, s[2:3] offset:320
	global_load_dword v118, v38, s[2:3] offset:384
	global_load_dword v119, v38, s[2:3] offset:448
	s_waitcnt vmcnt(7)
	v_mov_b32_e32 v39, v112
	v_pk_fma_f32 v[32:33], v[32:33], s[36:37], v[36:37] op_sel_hi:[1,0,0]
	s_nop 0
	v_mul_f32_e32 v28, v28, v39
	v_mul_f32_e32 v36, 0x4b800000, v33
	v_cmp_gt_f32_e64 s[4:5], s33, v33
	v_cmp_gt_f32_e32 vcc, s33, v32
	v_cvt_pk_bf16_f32 v28, v28, s0
	v_cndmask_b32_e64 v33, v33, v36, s[4:5]
	v_rsq_f32_e32 v33, v33
	s_nop 0
	v_mul_f32_e32 v36, 0x45800000, v33
	v_cndmask_b32_e64 v36, v33, v36, s[4:5]
	v_mul_f32_e32 v33, 0x4b800000, v32
	v_cndmask_b32_e32 v32, v32, v33, vcc
	v_rsq_f32_e32 v32, v32
	v_mul_f32_e32 v30, v30, v36
	v_mul_f32_e32 v30, v39, v30
	v_cvt_pk_bf16_f32 v30, v30, s0
	v_mul_f32_e32 v33, 0x45800000, v32
	v_cndmask_b32_e32 v37, v32, v33, vcc
	v_lshlrev_b64 v[32:33], 12, v[68:69]
	v_lshl_add_u64 v[32:33], s[38:39], 0, v[32:33]
	v_lshl_add_u64 v[32:33], v[32:33], 0, s[92:93]
	v_lshl_add_u64 v[32:33], v[32:33], 0, v[176:177]
	global_store_short v[32:33], v28, off offset:3072
	v_mul_f32_e32 v28, v29, v35
	v_mul_f32_e32 v28, v39, v28
	v_cvt_pk_bf16_f32 v40, v28, s0
	v_add_co_u32_e32 v28, vcc, s22, v32
	s_nop 1
	v_addc_co_u32_e32 v29, vcc, 0, v33, vcc
	global_store_short v[28:29], v40, off offset:3072
	v_add_co_u32_e32 v40, vcc, s31, v32
	s_nop 1
	v_addc_co_u32_e32 v41, vcc, 0, v33, vcc
	global_store_short v[40:41], v30, off offset:3072
	v_mul_f32_e32 v30, v31, v37
	v_mul_f32_e32 v30, v39, v30
	v_cvt_pk_bf16_f32 v39, v30, s0
	v_add_co_u32_e32 v30, vcc, s18, v32
	s_nop 1
	v_addc_co_u32_e32 v31, vcc, 0, v33, vcc
	global_store_short v[30:31], v39, off offset:3072
	s_waitcnt vmcnt(10)
	v_mov_b32_e32 v39, v113
	s_nop 0
	v_mul_f32_e32 v24, v24, v39
	v_cvt_pk_bf16_f32 v24, v24, s0
	global_store_short v[32:33], v24, off offset:3104
	v_mul_f32_e32 v24, v25, v35
	v_mul_f32_e32 v24, v24, v39
	v_cvt_pk_bf16_f32 v24, v24, s0
	global_store_short v[28:29], v24, off offset:3104
	v_mul_f32_e32 v24, v26, v36
	v_mul_f32_e32 v24, v39, v24
	v_cvt_pk_bf16_f32 v24, v24, s0
	global_store_short v[40:41], v24, off offset:3104
	v_mul_f32_e32 v24, v27, v37
	v_mul_f32_e32 v24, v39, v24
	v_cvt_pk_bf16_f32 v24, v24, s0
	global_store_short v[30:31], v24, off offset:3104
	s_waitcnt vmcnt(13)
	v_mov_b32_e32 v24, v114
	s_nop 0
	v_mul_f32_e32 v20, v20, v24
	v_cvt_pk_bf16_f32 v20, v20, s0
	global_store_short v[32:33], v20, off offset:3136
	v_mul_f32_e32 v20, v21, v35
	v_mul_f32_e32 v20, v20, v24
	v_cvt_pk_bf16_f32 v20, v20, s0
	global_store_short v[28:29], v20, off offset:3136
	v_mul_f32_e32 v20, v22, v36
	v_mul_f32_e32 v20, v20, v24
	v_cvt_pk_bf16_f32 v20, v20, s0
	global_store_short v[40:41], v20, off offset:3136
	v_mul_f32_e32 v20, v23, v37
	v_mul_f32_e32 v20, v20, v24
	v_cvt_pk_bf16_f32 v20, v20, s0
	global_store_short v[30:31], v20, off offset:3136
	s_waitcnt vmcnt(16)
	v_mov_b32_e32 v20, v115
	s_nop 0
	v_mul_f32_e32 v16, v16, v20
	v_cvt_pk_bf16_f32 v16, v16, s0
	global_store_short v[32:33], v16, off offset:3168
	v_mul_f32_e32 v16, v17, v35
	v_mul_f32_e32 v16, v16, v20
	v_cvt_pk_bf16_f32 v16, v16, s0
	global_store_short v[28:29], v16, off offset:3168
	v_mul_f32_e32 v16, v18, v36
	v_mul_f32_e32 v16, v16, v20
	v_cvt_pk_bf16_f32 v16, v16, s0
	global_store_short v[40:41], v16, off offset:3168
	v_mul_f32_e32 v16, v19, v37
	v_mul_f32_e32 v16, v16, v20
	v_cvt_pk_bf16_f32 v16, v16, s0
	global_store_short v[30:31], v16, off offset:3168
	s_waitcnt vmcnt(19)
	v_mov_b32_e32 v16, v116
	s_nop 0
	v_mul_f32_e32 v12, v12, v16
	v_cvt_pk_bf16_f32 v12, v12, s0
	global_store_short v[32:33], v12, off offset:3200
	v_mul_f32_e32 v12, v13, v35
	v_mul_f32_e32 v12, v12, v16
	v_cvt_pk_bf16_f32 v12, v12, s0
	global_store_short v[28:29], v12, off offset:3200
	v_mul_f32_e32 v12, v14, v36
	v_mul_f32_e32 v12, v12, v16
	v_cvt_pk_bf16_f32 v12, v12, s0
	global_store_short v[40:41], v12, off offset:3200
	v_mul_f32_e32 v12, v15, v37
	v_mul_f32_e32 v12, v12, v16
	v_cvt_pk_bf16_f32 v12, v12, s0
	global_store_short v[30:31], v12, off offset:3200
	s_waitcnt vmcnt(22)
	v_mov_b32_e32 v12, v117
	s_nop 0
	v_mul_f32_e32 v8, v8, v12
	v_cvt_pk_bf16_f32 v8, v8, s0
	global_store_short v[32:33], v8, off offset:3232
	v_mul_f32_e32 v8, v9, v35
	v_mul_f32_e32 v8, v8, v12
	v_cvt_pk_bf16_f32 v8, v8, s0
	global_store_short v[28:29], v8, off offset:3232
	v_mul_f32_e32 v8, v10, v36
	v_mul_f32_e32 v8, v8, v12
	v_cvt_pk_bf16_f32 v8, v8, s0
	global_store_short v[40:41], v8, off offset:3232
	v_mul_f32_e32 v8, v11, v37
	v_mul_f32_e32 v8, v8, v12
	v_cvt_pk_bf16_f32 v8, v8, s0
	global_store_short v[30:31], v8, off offset:3232
	s_waitcnt vmcnt(25)
	v_mov_b32_e32 v8, v118
	s_nop 0
	v_mul_f32_e32 v4, v4, v8
	v_cvt_pk_bf16_f32 v4, v4, s0
	global_store_short v[32:33], v4, off offset:3264
	v_mul_f32_e32 v4, v5, v35
	v_mul_f32_e32 v4, v4, v8
	v_cvt_pk_bf16_f32 v4, v4, s0
	global_store_short v[28:29], v4, off offset:3264
	v_mul_f32_e32 v4, v6, v36
	v_mul_f32_e32 v4, v4, v8
	v_cvt_pk_bf16_f32 v4, v4, s0
	global_store_short v[40:41], v4, off offset:3264
	v_mul_f32_e32 v4, v7, v37
	v_mul_f32_e32 v4, v4, v8
	v_cvt_pk_bf16_f32 v4, v4, s0
	global_store_short v[30:31], v4, off offset:3264
	s_waitcnt vmcnt(28)
	v_mov_b32_e32 v4, v119
	s_nop 0
	v_mul_f32_e32 v0, v0, v4
	v_cvt_pk_bf16_f32 v0, v0, s0
	global_store_short v[32:33], v0, off offset:3296
	v_mul_f32_e32 v0, v1, v35
	v_mul_f32_e32 v0, v0, v4
	v_cvt_pk_bf16_f32 v0, v0, s0
	global_store_short v[28:29], v0, off offset:3296
	v_mul_f32_e32 v0, v2, v36
	v_mul_f32_e32 v0, v0, v4
	v_cvt_pk_bf16_f32 v0, v0, s0
	global_store_short v[40:41], v0, off offset:3296
	v_mul_f32_e32 v0, v3, v37
	v_mul_f32_e32 v0, v0, v4
	v_cvt_pk_bf16_f32 v0, v0, s0
	global_store_short v[30:31], v0, off offset:3296
	s_cbranch_scc0 .LBB0_117

.LBB0_137:
	s_or_b64 exec, exec, s[2:3]
	v_max3_f32 v0, v25, s34, v24
	v_max3_f32 v0, v0, v27, v26
	v_max3_f32 v0, v0, v65, v64
	v_max3_f32 v0, v0, v61, v60
	v_max3_f32 v0, v0, v63, v62
	v_max3_f32 v0, v0, v57, v56
	v_max3_f32 v0, v0, v59, v58
	v_max3_f32 v0, v0, v53, v52
	v_max3_f32 v0, v0, v55, v54
	v_max3_f32 v0, v0, v49, v48
	v_max3_f32 v0, v0, v51, v50
	v_max3_f32 v0, v0, v45, v44
	v_max3_f32 v0, v0, v47, v46
	v_max3_f32 v0, v0, v41, v40
	v_max3_f32 v0, v0, v43, v42
	v_max3_f32 v0, v0, v37, v36
	v_max3_f32 v0, v0, v39, v38
	v_max3_f32 v0, v0, v32, v33
	v_max3_f32 v0, v0, v90, v89
	v_max3_f32 v0, v0, v92, v91
	v_max3_f32 v0, v0, v94, v93
	v_max3_f32 v0, v0, v96, v95
	v_max3_f32 v0, v0, v98, v97
	v_max3_f32 v0, v0, v100, v99
	v_max3_f32 v0, v0, v102, v101
	v_max3_f32 v0, v0, v104, v103
	v_max3_f32 v0, v0, v106, v105
	v_max3_f32 v0, v0, v108, v107
	v_and_b32_e32 v2, 64, v225
	v_max3_f32 v0, v0, v110, v109
	v_xor_b32_e32 v1, 16, v225
	v_add_u32_e32 v67, 64, v2
	v_max3_f32 v0, v0, v81, v79
	v_cmp_lt_i32_e32 vcc, v1, v67
	v_max3_f32 v0, v0, v111, v84
	v_max3_f32 v0, v0, v112, v86
	v_cndmask_b32_e32 v1, v225, v1, vcc
	v_lshlrev_b32_e32 v78, 2, v1
	ds_bpermute_b32 v1, v78, v0
	v_lshrrev_b32_e32 v66, 1, v82
	v_lshl_or_b32 v176, v83, 14, v68
	s_movk_i32 s7, 0x1000
	s_waitcnt lgkmcnt(0)
	v_max_f32_e32 v1, v1, v1
	v_max_f32_e32 v0, v0, v1
	v_xor_b32_e32 v1, 32, v225
	v_cmp_lt_i32_e32 vcc, v1, v67
	s_nop 1
	v_cndmask_b32_e32 v1, v225, v1, vcc
	v_lshlrev_b32_e32 v82, 2, v1
	ds_bpermute_b32 v1, v82, v0
	s_waitcnt lgkmcnt(0)
	v_max_f32_e32 v1, v1, v1
	v_max_f32_e32 v87, v0, v1
	v_sub_f32_e32 v0, v25, v87
	v_mul_f32_e32 v0, 0x3fb8aa3b, v0
	v_sub_f32_e32 v1, v24, v87
	v_exp_f32_e32 v0, v0
	v_mul_f32_e32 v1, 0x3fb8aa3b, v1
	v_exp_f32_e32 v1, v1
	v_sub_f32_e32 v5, v65, v87
	v_add_f32_e32 v2, 0, v0
	v_mul_f32_e32 v5, 0x3fb8aa3b, v5
	v_add_f32_e32 v3, v1, v2
	v_sub_f32_e32 v2, v27, v87
	v_mul_f32_e32 v2, 0x3fb8aa3b, v2
	v_exp_f32_e32 v2, v2
	v_exp_f32_e32 v6, v5
	v_sub_f32_e32 v5, v64, v87
	v_mul_f32_e32 v5, 0x3fb8aa3b, v5
	v_add_f32_e32 v4, v2, v3
	v_sub_f32_e32 v3, v26, v87
	v_mul_f32_e32 v3, 0x3fb8aa3b, v3
	v_exp_f32_e32 v3, v3
	v_exp_f32_e32 v7, v5
	v_sub_f32_e32 v5, v61, v87
	v_mul_f32_e32 v5, 0x3fb8aa3b, v5
	v_exp_f32_e32 v10, v5
	v_sub_f32_e32 v5, v60, v87
	v_mul_f32_e32 v5, 0x3fb8aa3b, v5
	v_add_f32_e32 v4, v3, v4
	v_exp_f32_e32 v11, v5
	v_add_f32_e32 v4, v6, v4
	v_add_f32_e32 v4, v7, v4
	v_add_f32_e32 v4, v10, v4
	v_add_f32_e32 v5, v11, v4
	v_sub_f32_e32 v4, v63, v87
	v_mul_f32_e32 v4, 0x3fb8aa3b, v4
	v_exp_f32_e32 v4, v4
	v_sub_f32_e32 v13, v59, v87
	v_mul_f32_e32 v13, 0x3fb8aa3b, v13
	v_exp_f32_e32 v14, v13
	v_add_f32_e32 v8, v4, v5
	v_sub_f32_e32 v5, v62, v87
	v_mul_f32_e32 v5, 0x3fb8aa3b, v5
	v_exp_f32_e32 v5, v5
	v_sub_f32_e32 v13, v58, v87
	v_mul_f32_e32 v13, 0x3fb8aa3b, v13
	v_exp_f32_e32 v15, v13
	v_add_f32_e32 v9, v5, v8
	v_sub_f32_e32 v8, v57, v87
	v_mul_f32_e32 v8, 0x3fb8aa3b, v8
	v_exp_f32_e32 v8, v8
	v_sub_f32_e32 v13, v53, v87
	v_mul_f32_e32 v13, 0x3fb8aa3b, v13
	v_exp_f32_e32 v18, v13
	v_add_f32_e32 v12, v8, v9
	v_sub_f32_e32 v9, v56, v87
	v_mul_f32_e32 v9, 0x3fb8aa3b, v9
	v_exp_f32_e32 v9, v9
	v_sub_f32_e32 v13, v52, v87
	v_mul_f32_e32 v13, 0x3fb8aa3b, v13
	v_exp_f32_e32 v19, v13
	v_add_f32_e32 v12, v9, v12
	v_add_f32_e32 v12, v14, v12
	v_add_f32_e32 v12, v15, v12
	v_add_f32_e32 v12, v18, v12
	v_add_f32_e32 v13, v19, v12
	v_sub_f32_e32 v12, v55, v87
	v_mul_f32_e32 v12, 0x3fb8aa3b, v12
	v_exp_f32_e32 v12, v12
	v_sub_f32_e32 v21, v51, v87
	v_mul_f32_e32 v21, 0x3fb8aa3b, v21
	v_exp_f32_e32 v22, v21
	v_add_f32_e32 v16, v12, v13
	v_sub_f32_e32 v13, v54, v87
	v_mul_f32_e32 v13, 0x3fb8aa3b, v13
	v_exp_f32_e32 v13, v13
	v_sub_f32_e32 v21, v50, v87
	v_mul_f32_e32 v21, 0x3fb8aa3b, v21
	v_exp_f32_e32 v23, v21
	v_add_f32_e32 v17, v13, v16
	v_sub_f32_e32 v16, v49, v87
	v_mul_f32_e32 v16, 0x3fb8aa3b, v16
	v_exp_f32_e32 v16, v16
	v_sub_f32_e32 v21, v45, v87
	v_mul_f32_e32 v21, 0x3fb8aa3b, v21
	v_exp_f32_e32 v26, v21
	v_add_f32_e32 v20, v16, v17
	v_sub_f32_e32 v17, v48, v87
	v_mul_f32_e32 v17, 0x3fb8aa3b, v17
	v_exp_f32_e32 v17, v17
	v_sub_f32_e32 v21, v44, v87
	v_mul_f32_e32 v21, 0x3fb8aa3b, v21
	v_exp_f32_e32 v27, v21
	v_add_f32_e32 v20, v17, v20
	v_add_f32_e32 v20, v22, v20
	v_add_f32_e32 v20, v23, v20
	v_add_f32_e32 v20, v26, v20
	v_add_f32_e32 v21, v27, v20
	v_sub_f32_e32 v20, v47, v87
	v_mul_f32_e32 v20, 0x3fb8aa3b, v20
	v_exp_f32_e32 v20, v20
	v_sub_f32_e32 v29, v43, v87
	v_mul_f32_e32 v29, 0x3fb8aa3b, v29
	v_exp_f32_e32 v30, v29
	v_add_f32_e32 v24, v20, v21
	v_sub_f32_e32 v21, v46, v87
	v_mul_f32_e32 v21, 0x3fb8aa3b, v21
	v_exp_f32_e32 v21, v21
	v_sub_f32_e32 v29, v42, v87
	v_mul_f32_e32 v29, 0x3fb8aa3b, v29
	v_exp_f32_e32 v31, v29
	v_add_f32_e32 v25, v21, v24
	v_sub_f32_e32 v24, v41, v87
	v_mul_f32_e32 v24, 0x3fb8aa3b, v24
	v_exp_f32_e32 v24, v24
	v_sub_f32_e32 v29, v37, v87
	v_mul_f32_e32 v29, 0x3fb8aa3b, v29
	v_exp_f32_e32 v34, v29
	v_add_f32_e32 v28, v24, v25
	v_sub_f32_e32 v25, v40, v87
	v_mul_f32_e32 v25, 0x3fb8aa3b, v25
	v_exp_f32_e32 v25, v25
	v_sub_f32_e32 v29, v36, v87
	v_mul_f32_e32 v29, 0x3fb8aa3b, v29
	v_exp_f32_e32 v35, v29
	v_add_f32_e32 v28, v25, v28
	v_add_f32_e32 v28, v30, v28
	v_add_f32_e32 v28, v31, v28
	v_add_f32_e32 v28, v34, v28
	v_add_f32_e32 v29, v35, v28
	v_sub_f32_e32 v28, v39, v87
	v_mul_f32_e32 v28, 0x3fb8aa3b, v28
	v_exp_f32_e32 v28, v28
	v_sub_f32_e32 v37, v90, v87
	v_sub_f32_e32 v32, v32, v87
	v_mul_f32_e32 v37, 0x3fb8aa3b, v37
	v_add_f32_e32 v36, v28, v29
	v_sub_f32_e32 v29, v38, v87
	v_mul_f32_e32 v29, 0x3fb8aa3b, v29
	v_exp_f32_e32 v29, v29
	v_mul_f32_e32 v32, 0x3fb8aa3b, v32
	v_sub_f32_e32 v33, v33, v87
	v_exp_f32_e32 v38, v37
	v_sub_f32_e32 v37, v89, v87
	v_exp_f32_e32 v32, v32
	v_mul_f32_e32 v33, 0x3fb8aa3b, v33
	v_mul_f32_e32 v37, 0x3fb8aa3b, v37
	v_exp_f32_e32 v33, v33
	v_exp_f32_e32 v39, v37
	v_sub_f32_e32 v37, v92, v87
	v_mul_f32_e32 v37, 0x3fb8aa3b, v37
	v_add_f32_e32 v36, v29, v36
	v_exp_f32_e32 v42, v37
	v_sub_f32_e32 v37, v91, v87
	v_add_f32_e32 v36, v32, v36
	v_mul_f32_e32 v37, 0x3fb8aa3b, v37
	v_add_f32_e32 v36, v33, v36
	v_exp_f32_e32 v43, v37
	v_add_f32_e32 v36, v38, v36
	v_add_f32_e32 v36, v39, v36
	v_add_f32_e32 v36, v42, v36
	v_add_f32_e32 v37, v43, v36
	v_sub_f32_e32 v36, v94, v87
	v_mul_f32_e32 v36, 0x3fb8aa3b, v36
	v_exp_f32_e32 v36, v36
	v_sub_f32_e32 v45, v98, v87
	v_mul_f32_e32 v45, 0x3fb8aa3b, v45
	v_exp_f32_e32 v46, v45
	v_add_f32_e32 v40, v36, v37
	v_sub_f32_e32 v37, v93, v87
	v_mul_f32_e32 v37, 0x3fb8aa3b, v37
	v_exp_f32_e32 v37, v37
	v_sub_f32_e32 v45, v97, v87
	v_mul_f32_e32 v45, 0x3fb8aa3b, v45
	v_exp_f32_e32 v47, v45
	v_add_f32_e32 v41, v37, v40
	v_sub_f32_e32 v40, v96, v87
	v_mul_f32_e32 v40, 0x3fb8aa3b, v40
	v_exp_f32_e32 v40, v40
	v_sub_f32_e32 v45, v100, v87
	v_mul_f32_e32 v45, 0x3fb8aa3b, v45
	v_exp_f32_e32 v50, v45
	v_add_f32_e32 v44, v40, v41
	v_sub_f32_e32 v41, v95, v87
	v_mul_f32_e32 v41, 0x3fb8aa3b, v41
	v_exp_f32_e32 v41, v41
	v_sub_f32_e32 v45, v99, v87
	v_mul_f32_e32 v45, 0x3fb8aa3b, v45
	v_exp_f32_e32 v51, v45
	v_add_f32_e32 v44, v41, v44
	v_add_f32_e32 v44, v46, v44
	v_add_f32_e32 v44, v47, v44
	v_add_f32_e32 v44, v50, v44
	v_add_f32_e32 v45, v51, v44
	v_sub_f32_e32 v44, v102, v87
	v_mul_f32_e32 v44, 0x3fb8aa3b, v44
	v_exp_f32_e32 v44, v44
	v_sub_f32_e32 v53, v106, v87
	v_mul_f32_e32 v53, 0x3fb8aa3b, v53
	v_exp_f32_e32 v54, v53
	v_add_f32_e32 v48, v44, v45
	v_sub_f32_e32 v45, v101, v87
	v_mul_f32_e32 v45, 0x3fb8aa3b, v45
	v_exp_f32_e32 v45, v45
	v_sub_f32_e32 v53, v105, v87
	v_mul_f32_e32 v53, 0x3fb8aa3b, v53
	v_exp_f32_e32 v55, v53
	v_add_f32_e32 v49, v45, v48
	v_sub_f32_e32 v48, v104, v87
	v_mul_f32_e32 v48, 0x3fb8aa3b, v48
	v_exp_f32_e32 v48, v48
	v_sub_f32_e32 v53, v108, v87
	v_mul_f32_e32 v53, 0x3fb8aa3b, v53
	v_exp_f32_e32 v58, v53
	v_add_f32_e32 v52, v48, v49
	v_sub_f32_e32 v49, v103, v87
	v_mul_f32_e32 v49, 0x3fb8aa3b, v49
	v_exp_f32_e32 v49, v49
	v_sub_f32_e32 v53, v107, v87
	v_mul_f32_e32 v53, 0x3fb8aa3b, v53
	v_exp_f32_e32 v59, v53
	v_add_f32_e32 v52, v49, v52
	v_add_f32_e32 v52, v54, v52
	v_add_f32_e32 v52, v55, v52
	v_add_f32_e32 v52, v58, v52
	v_add_f32_e32 v53, v59, v52
	v_sub_f32_e32 v52, v110, v87
	v_mul_f32_e32 v52, 0x3fb8aa3b, v52
	v_exp_f32_e32 v52, v52
	s_nop 0
	v_add_f32_e32 v56, v52, v53
	v_sub_f32_e32 v53, v109, v87
	v_mul_f32_e32 v53, 0x3fb8aa3b, v53
	v_exp_f32_e32 v53, v53
	s_nop 0
	v_add_f32_e32 v57, v53, v56
	v_sub_f32_e32 v56, v81, v87
	v_mul_f32_e32 v56, 0x3fb8aa3b, v56
	v_exp_f32_e32 v56, v56
	s_nop 0
	v_add_f32_e32 v60, v56, v57
	v_sub_f32_e32 v57, v79, v87
	v_mul_f32_e32 v57, 0x3fb8aa3b, v57
	v_exp_f32_e32 v57, v57
	s_nop 0
	v_add_f32_e32 v61, v57, v60
	v_sub_f32_e32 v60, v111, v87
	v_mul_f32_e32 v60, 0x3fb8aa3b, v60
	v_exp_f32_e32 v60, v60
	s_nop 0
	v_add_f32_e32 v62, v60, v61
	v_sub_f32_e32 v61, v84, v87
	v_mul_f32_e32 v61, 0x3fb8aa3b, v61
	v_exp_f32_e32 v61, v61
	s_nop 0
	v_add_f32_e32 v63, v61, v62
	v_sub_f32_e32 v62, v112, v87
	v_mul_f32_e32 v62, 0x3fb8aa3b, v62
	v_exp_f32_e32 v62, v62
	s_nop 0
	v_add_f32_e32 v64, v62, v63
	v_sub_f32_e32 v63, v86, v87
	v_mul_f32_e32 v63, 0x3fb8aa3b, v63
	v_exp_f32_e32 v63, v63
	s_nop 0
	v_add_f32_e32 v64, v63, v64
	ds_bpermute_b32 v65, v78, v64
	s_waitcnt lgkmcnt(0)
	v_add_f32_e32 v64, v64, v65
	ds_bpermute_b32 v65, v82, v64
	s_waitcnt lgkmcnt(0)
	v_add_f32_e32 v64, v64, v65
	v_div_scale_f32 v65, s[2:3], v64, v64, 1.0
	v_rcp_f32_e32 v78, v65
	s_movk_i32 s2, 0x480
	v_fma_f32 v79, -v65, v78, 1.0
	v_fmac_f32_e32 v78, v79, v78
	v_div_scale_f32 v79, vcc, 1.0, v64, 1.0
	v_mul_f32_e32 v81, v79, v78
	v_fma_f32 v82, -v65, v81, v79
	v_fmac_f32_e32 v81, v82, v78
	v_fma_f32 v65, -v65, v81, v79
	v_div_fmas_f32 v65, v65, v78, v81
	v_div_fixup_f32 v64, v65, v64, 1.0
	v_lshrrev_b32_e32 v65, 3, v77
	v_add_u32_e32 v65, v65, v83
	v_pk_mul_f32 v[2:3], v[2:3], v[64:65] op_sel_hi:[1,0]
	v_pk_mul_f32 v[0:1], v[0:1], v[64:65] op_sel_hi:[1,0]
	v_pk_mul_f32 v[6:7], v[6:7], v[64:65] op_sel_hi:[1,0]
	v_cvt_pk_bf16_f32 v0, v0, v1
	v_cvt_pk_bf16_f32 v1, v2, v3
	v_cvt_pk_bf16_f32 v2, v6, v7
	v_lshl_add_u32 v6, v70, 3, v65
	v_bitop3_b32 v6, v6, v66, 7 bitop3:0x78
	v_lshl_add_u32 v6, v6, 4, s27
	v_mad_u32_u24 v7, v85, s2, v6
	v_mad_u32_u24 v70, v85, s2, v227
	ds_read_b128 v[86:89], v7
	v_add_u32_e32 v7, v6, v70
	v_mad_u32_u24 v81, v85, s2, v252
	v_mad_u32_u24 v82, v85, s2, v224
	ds_read_b128 v[90:93], v7
	v_add_u32_e32 v7, v6, v81
	v_add_u32_e32 v6, v6, v82
	v_pk_mul_f32 v[10:11], v[10:11], v[64:65] op_sel_hi:[1,0]
	ds_read_b128 v[94:97], v7
	ds_read_b128 v[98:101], v6
	v_pk_mul_f32 v[6:7], v[8:9], v[64:65] op_sel_hi:[1,0]
	v_pk_mul_f32 v[4:5], v[4:5], v[64:65] op_sel_hi:[1,0]
	v_pk_mul_f32 v[8:9], v[18:19], v[64:65] op_sel_hi:[1,0]
	v_cvt_pk_bf16_f32 v3, v10, v11
	v_cvt_pk_bf16_f32 v4, v4, v5
	v_cvt_pk_bf16_f32 v5, v6, v7
	v_cvt_pk_bf16_f32 v7, v8, v9
	v_lshl_add_u32 v8, v76, 3, v65
	v_bitop3_b32 v8, v8, v66, 7 bitop3:0x78
	v_pk_mul_f32 v[10:11], v[14:15], v[64:65] op_sel_hi:[1,0]
	v_lshl_add_u32 v14, v8, 4, s27
	v_mad_u32_u24 v8, v85, s2, v14
	v_add_u32_e32 v15, v14, v70
	v_cvt_pk_bf16_f32 v6, v10, v11
	ds_read_b128 v[8:11], v8
	ds_read_b128 v[76:79], v15
	s_waitcnt lgkmcnt(5)
	v_mfma_f32_16x16x32_bf16 v[86:89], v[0:3], v[86:89], 0
	v_add_u32_e32 v15, v14, v81
	v_add_u32_e32 v14, v14, v82
	s_waitcnt lgkmcnt(4)
	v_mfma_f32_16x16x32_bf16 v[90:93], v[0:3], v[90:93], 0
	s_waitcnt lgkmcnt(0)
	v_mfma_f32_16x16x32_bf16 v[76:79], v[4:7], v[76:79], v[90:93]
	v_mfma_f32_16x16x32_bf16 v[94:97], v[0:3], v[94:97], 0
	s_nop 4
	ds_read_b128 v[90:93], v14
	v_mfma_f32_16x16x32_bf16 v[8:11], v[4:7], v[8:11], v[86:89]
	s_nop 2
	ds_read_b128 v[86:89], v15
	v_mfma_f32_16x16x32_bf16 v[0:3], v[0:3], v[98:101], 0
	v_mul_f32_e64 v14, v22, v64
	v_mul_f32_e64 v15, v23, v64
	s_waitcnt lgkmcnt(0)
	v_mfma_f32_16x16x32_bf16 v[86:89], v[4:7], v[86:89], v[94:97]
	v_mfma_f32_16x16x32_bf16 v[0:3], v[4:7], v[90:93], v[0:3]
	v_mul_f32_e64 v6, v16, v64
	v_mul_f32_e64 v7, v17, v64
	v_pk_mul_f32 v[4:5], v[12:13], v[64:65] op_sel_hi:[1,0]
	v_pk_mul_f32 v[12:13], v[26:27], v[64:65] op_sel_hi:[1,0]
	v_cvt_pk_bf16_f32 v4, v4, v5
	v_cvt_pk_bf16_f32 v5, v6, v7
	v_cvt_pk_bf16_f32 v7, v12, v13
	v_lshl_add_u32 v12, v75, 3, v65
	v_bitop3_b32 v12, v12, v66, 7 bitop3:0x78
	v_lshl_add_u32 v22, v12, 4, s27
	v_mad_u32_u24 v12, v85, s2, v22
	v_cvt_pk_bf16_f32 v6, v14, v15
	ds_read_b128 v[12:15], v12
	v_add_u32_e32 v16, v22, v81
	ds_read_b128 v[16:19], v16
	s_waitcnt lgkmcnt(1)
	v_mfma_f32_16x16x32_bf16 v[8:11], v[4:7], v[12:15], v[8:11]
	v_add_u32_e32 v12, v22, v70
	ds_read_b128 v[12:15], v12
	v_add_u32_e32 v22, v22, v82
	s_waitcnt lgkmcnt(0)
	v_mfma_f32_16x16x32_bf16 v[12:15], v[4:7], v[12:15], v[76:79]
	s_nop 2
	ds_read_b128 v[76:79], v22
	v_pk_mul_f32 v[22:23], v[30:31], v[64:65] op_sel_hi:[1,0]
	v_mfma_f32_16x16x32_bf16 v[16:19], v[4:7], v[16:19], v[86:89]
	s_waitcnt lgkmcnt(0)
	v_mfma_f32_16x16x32_bf16 v[0:3], v[4:7], v[76:79], v[0:3]
	v_mul_f32_e64 v6, v24, v64
	v_mul_f32_e64 v7, v25, v64
	v_pk_mul_f32 v[4:5], v[20:21], v[64:65] op_sel_hi:[1,0]
	v_pk_mul_f32 v[20:21], v[34:35], v[64:65] op_sel_hi:[1,0]
	v_cvt_pk_bf16_f32 v4, v4, v5
	v_cvt_pk_bf16_f32 v5, v6, v7
	v_cvt_pk_bf16_f32 v7, v20, v21
	v_lshl_add_u32 v20, v74, 3, v65
	v_bitop3_b32 v20, v20, v66, 7 bitop3:0x78
	v_lshl_add_u32 v24, v20, 4, s27
	v_mad_u32_u24 v20, v85, s2, v24
	v_cvt_pk_bf16_f32 v6, v22, v23
	ds_read_b128 v[20:23], v20
	s_waitcnt lgkmcnt(0)
	v_mfma_f32_16x16x32_bf16 v[8:11], v[4:7], v[20:23], v[8:11]
	v_add_u32_e32 v20, v24, v70
	ds_read_b128 v[20:23], v20
	s_waitcnt lgkmcnt(0)
	v_mfma_f32_16x16x32_bf16 v[12:15], v[4:7], v[20:23], v[12:15]
	v_add_u32_e32 v20, v24, v81
	ds_read_b128 v[20:23], v20
	s_waitcnt lgkmcnt(0)
	v_mfma_f32_16x16x32_bf16 v[16:19], v[4:7], v[20:23], v[16:19]
	v_add_u32_e32 v20, v24, v82
	ds_read_b128 v[20:23], v20
	s_waitcnt lgkmcnt(0)
	v_mfma_f32_16x16x32_bf16 v[0:3], v[4:7], v[20:23], v[0:3]
	v_mul_f32_e64 v6, v32, v64
	v_mul_f32_e64 v7, v33, v64
	v_pk_mul_f32 v[4:5], v[28:29], v[64:65] op_sel_hi:[1,0]
	v_pk_mul_f32 v[20:21], v[42:43], v[64:65] op_sel_hi:[1,0]
	v_cvt_pk_bf16_f32 v4, v4, v5
	v_cvt_pk_bf16_f32 v5, v6, v7
	v_cvt_pk_bf16_f32 v7, v20, v21
	v_lshl_add_u32 v20, v73, 3, v65
	v_bitop3_b32 v20, v20, v66, 7 bitop3:0x78
	v_lshl_add_u32 v24, v20, 4, s27
	v_pk_mul_f32 v[22:23], v[38:39], v[64:65] op_sel_hi:[1,0]
	v_mad_u32_u24 v20, v85, s2, v24
	v_cvt_pk_bf16_f32 v6, v22, v23
	ds_read_b128 v[20:23], v20
	s_waitcnt lgkmcnt(0)
	v_mfma_f32_16x16x32_bf16 v[8:11], v[4:7], v[20:23], v[8:11]
	v_add_u32_e32 v20, v24, v70
	ds_read_b128 v[20:23], v20
	s_waitcnt lgkmcnt(0)
	v_mfma_f32_16x16x32_bf16 v[12:15], v[4:7], v[20:23], v[12:15]
	v_add_u32_e32 v20, v24, v81
	ds_read_b128 v[20:23], v20
	s_waitcnt lgkmcnt(0)
	v_mfma_f32_16x16x32_bf16 v[16:19], v[4:7], v[20:23], v[16:19]
	v_add_u32_e32 v20, v24, v82
	ds_read_b128 v[20:23], v20
	s_waitcnt lgkmcnt(0)
	v_mfma_f32_16x16x32_bf16 v[0:3], v[4:7], v[20:23], v[0:3]
	v_mul_f32_e64 v6, v40, v64
	v_mul_f32_e64 v7, v41, v64
	v_pk_mul_f32 v[4:5], v[36:37], v[64:65] op_sel_hi:[1,0]
	v_pk_mul_f32 v[20:21], v[50:51], v[64:65] op_sel_hi:[1,0]
	v_cvt_pk_bf16_f32 v4, v4, v5
	v_cvt_pk_bf16_f32 v5, v6, v7
	v_cvt_pk_bf16_f32 v7, v20, v21
	v_lshl_add_u32 v20, v72, 3, v65
	v_bitop3_b32 v20, v20, v66, 7 bitop3:0x78
	v_lshl_add_u32 v24, v20, 4, s27
	v_pk_mul_f32 v[22:23], v[46:47], v[64:65] op_sel_hi:[1,0]
	v_mad_u32_u24 v20, v85, s2, v24
	v_cvt_pk_bf16_f32 v6, v22, v23
	ds_read_b128 v[20:23], v20
	s_waitcnt lgkmcnt(0)
	v_mfma_f32_16x16x32_bf16 v[8:11], v[4:7], v[20:23], v[8:11]
	v_add_u32_e32 v20, v24, v70
	ds_read_b128 v[20:23], v20
	s_waitcnt lgkmcnt(0)
	v_mfma_f32_16x16x32_bf16 v[12:15], v[4:7], v[20:23], v[12:15]
	v_add_u32_e32 v20, v24, v81
	ds_read_b128 v[20:23], v20
	s_waitcnt lgkmcnt(0)
	v_mfma_f32_16x16x32_bf16 v[16:19], v[4:7], v[20:23], v[16:19]
	v_add_u32_e32 v20, v24, v82
	ds_read_b128 v[20:23], v20
	s_waitcnt lgkmcnt(0)
	v_mfma_f32_16x16x32_bf16 v[0:3], v[4:7], v[20:23], v[0:3]
	v_mul_f32_e64 v6, v48, v64
	v_mul_f32_e64 v7, v49, v64
	v_pk_mul_f32 v[4:5], v[44:45], v[64:65] op_sel_hi:[1,0]
	v_pk_mul_f32 v[20:21], v[58:59], v[64:65] op_sel_hi:[1,0]
	v_cvt_pk_bf16_f32 v4, v4, v5
	v_cvt_pk_bf16_f32 v5, v6, v7
	v_cvt_pk_bf16_f32 v7, v20, v21
	v_lshl_add_u32 v20, v71, 3, v65
	v_bitop3_b32 v20, v20, v66, 7 bitop3:0x78
	v_lshl_add_u32 v24, v20, 4, s27
	v_pk_mul_f32 v[22:23], v[54:55], v[64:65] op_sel_hi:[1,0]
	v_mad_u32_u24 v20, v85, s2, v24
	v_cvt_pk_bf16_f32 v6, v22, v23
	ds_read_b128 v[20:23], v20
	s_waitcnt lgkmcnt(0)
	v_mfma_f32_16x16x32_bf16 v[8:11], v[4:7], v[20:23], v[8:11]
	v_add_u32_e32 v20, v24, v70
	ds_read_b128 v[20:23], v20
	s_waitcnt lgkmcnt(0)
	v_mfma_f32_16x16x32_bf16 v[20:23], v[4:7], v[20:23], v[12:15]
	s_nop 2
	v_add_u32_e32 v12, v24, v81
	ds_read_b128 v[12:15], v12
	s_waitcnt lgkmcnt(0)
	v_mfma_f32_16x16x32_bf16 v[16:19], v[4:7], v[12:15], v[16:19]
	v_add_u32_e32 v12, v24, v82
	ds_read_b128 v[12:15], v12
	s_waitcnt lgkmcnt(0)
	v_mfma_f32_16x16x32_bf16 v[0:3], v[4:7], v[12:15], v[0:3]
	v_mul_f32_e64 v4, v56, v64
	v_mul_f32_e64 v5, v57, v64
	v_pk_mul_f32 v[6:7], v[52:53], v[64:65] op_sel_hi:[1,0]
	v_cvt_pk_bf16_f32 v25, v4, v5
	v_lshl_add_u32 v4, v69, 3, v65
	v_bitop3_b32 v4, v4, v66, 7 bitop3:0x78
	v_lshl_add_u32 v28, v4, 4, s27
	v_pk_mul_f32 v[12:13], v[62:63], v[64:65] op_sel_hi:[1,0]
	v_pk_mul_f32 v[14:15], v[60:61], v[64:65] op_sel_hi:[1,0]
	v_mad_u32_u24 v4, v85, s2, v28
	v_cvt_pk_bf16_f32 v24, v6, v7
	v_cvt_pk_bf16_f32 v26, v14, v15
	v_cvt_pk_bf16_f32 v27, v12, v13
	ds_read_b128 v[4:7], v4
	s_mov_b32 s2, 0x3c800000
	s_waitcnt lgkmcnt(0)
	v_mfma_f32_16x16x32_bf16 v[12:15], v[24:27], v[4:7], v[8:11]
	v_add_u32_e32 v4, v28, v70
	ds_read_b128 v[4:7], v4
	s_waitcnt lgkmcnt(0)
	v_mfma_f32_16x16x32_bf16 v[8:11], v[24:27], v[4:7], v[20:23]
	v_add_u32_e32 v4, v28, v81
	ds_read_b128 v[4:7], v4
	s_nop 1
	v_mov_b32_e32 v20, v13
	s_waitcnt lgkmcnt(0)
	v_mfma_f32_16x16x32_bf16 v[4:7], v[24:27], v[4:7], v[16:19]
	s_nop 2
	v_add_u32_e32 v16, v28, v82
	ds_read_b128 v[16:19], v16
	v_mov_b32_e32 v21, v9
	s_waitcnt lgkmcnt(0)
	v_mfma_f32_16x16x32_bf16 v[0:3], v[24:27], v[16:19], v[0:3]
	v_xor_b32_e32 v16, 1, v225
	v_cmp_lt_i32_e32 vcc, v16, v67
	v_mov_b32_e32 v17, v8
	v_mov_b32_e32 v18, v4
	v_cndmask_b32_e32 v16, v225, v16, vcc
	v_lshlrev_b32_e32 v30, 2, v16
	v_xor_b32_e32 v16, 2, v225
	v_cmp_lt_i32_e32 vcc, v16, v67
	v_mov_b32_e32 v19, v0
	v_pk_mul_f32 v[20:21], v[20:21], v[20:21]
	v_cndmask_b32_e32 v16, v225, v16, vcc
	v_lshlrev_b32_e32 v31, 2, v16
	v_xor_b32_e32 v16, 4, v225
	v_cmp_lt_i32_e32 vcc, v16, v67
	v_mov_b32_e32 v22, v5
	v_mov_b32_e32 v23, v1
	v_cndmask_b32_e32 v16, v225, v16, vcc
	v_lshlrev_b32_e32 v32, 2, v16
	v_xor_b32_e32 v16, 8, v225
	v_cmp_lt_i32_e32 vcc, v16, v67
	v_pk_mul_f32 v[18:19], v[18:19], v[18:19]
	v_pk_mul_f32 v[22:23], v[22:23], v[22:23]
	v_cndmask_b32_e32 v16, v225, v16, vcc
	v_lshlrev_b32_e32 v33, 2, v16
	v_mov_b32_e32 v16, v12
	v_pk_mul_f32 v[16:17], v[16:17], v[16:17]
	v_mov_b32_e32 v24, v20
	v_mov_b32_e32 v25, v16
	v_mov_b32_e32 v16, v21
	v_pk_add_f32 v[16:17], v[24:25], v[16:17]
	v_mov_b32_e32 v20, v22
	v_mov_b32_e32 v21, v18
	v_pk_add_f32 v[16:17], v[16:17], v[20:21]
	v_mov_b32_e32 v18, v23
	v_pk_add_f32 v[16:17], v[16:17], v[18:19]
	ds_bpermute_b32 v19, v30, v17
	ds_bpermute_b32 v18, v30, v16
	v_mov_b32_e32 v24, v15
	v_mov_b32_e32 v25, v11
	v_mov_b32_e32 v22, v6
	v_mov_b32_e32 v23, v2
	s_waitcnt lgkmcnt(0)
	v_pk_add_f32 v[16:17], v[16:17], v[18:19]
	ds_bpermute_b32 v19, v31, v17
	ds_bpermute_b32 v18, v31, v16
	v_pk_mul_f32 v[24:25], v[24:25], v[24:25]
	v_mov_b32_e32 v26, v7
	v_mov_b32_e32 v27, v3
	v_pk_mul_f32 v[22:23], v[22:23], v[22:23]
	s_waitcnt lgkmcnt(0)
	v_pk_add_f32 v[16:17], v[16:17], v[18:19]
	ds_bpermute_b32 v19, v32, v17
	ds_bpermute_b32 v18, v32, v16
	v_pk_mul_f32 v[26:27], v[26:27], v[26:27]
	v_mov_b32_e32 v28, v24
	v_mov_b32_e32 v24, v26
	v_ashrrev_i32_e32 v81, 31, v80
	s_waitcnt lgkmcnt(0)
	v_pk_add_f32 v[16:17], v[16:17], v[18:19]
	ds_bpermute_b32 v19, v33, v17
	ds_bpermute_b32 v18, v33, v16
	s_waitcnt lgkmcnt(0)
	v_pk_add_f32 v[16:17], v[16:17], v[18:19]
	v_mov_b64_e32 v[18:19], s[36:37]
	v_pk_fma_f32 v[16:17], v[16:17], s[2:3], v[18:19] op_sel_hi:[1,0,0]
	s_nop 0
	v_mul_f32_e32 v20, 0x4b800000, v17
	v_cmp_gt_f32_e64 s[4:5], s33, v17
	v_cmp_gt_f32_e32 vcc, s33, v16
	s_nop 0
	v_cndmask_b32_e64 v17, v17, v20, s[4:5]
	v_rsq_f32_e32 v17, v17
	s_nop 0
	v_mul_f32_e32 v20, 0x45800000, v17
	v_cndmask_b32_e64 v20, v17, v20, s[4:5]
	v_mul_f32_e32 v17, 0x4b800000, v16
	v_cndmask_b32_e32 v16, v16, v17, vcc
	v_rsq_f32_e32 v16, v16
	v_mul_f32_e32 v12, v12, v20
	v_mul_f32_e32 v8, v8, v20
	v_mul_f32_e32 v4, v4, v20
	v_mul_f32_e32 v17, 0x45800000, v16
	v_cndmask_b32_e32 v21, v16, v17, vcc
	v_mov_b32_e32 v16, v14
	v_mov_b32_e32 v17, v10
	v_pk_mul_f32 v[16:17], v[16:17], v[16:17]
	v_mul_f32_e32 v0, v0, v20
	v_mov_b32_e32 v29, v16
	v_mov_b32_e32 v16, v25
	v_pk_add_f32 v[16:17], v[28:29], v[16:17]
	v_mov_b32_e32 v25, v22
	v_pk_add_f32 v[16:17], v[16:17], v[24:25]
	v_mov_b32_e32 v22, v27
	v_pk_add_f32 v[16:17], v[16:17], v[22:23]
	ds_bpermute_b32 v23, v30, v17
	ds_bpermute_b32 v22, v30, v16
	v_lshlrev_b32_e32 v24, 2, v85
	s_waitcnt lgkmcnt(0)
	v_pk_add_f32 v[16:17], v[16:17], v[22:23]
	ds_bpermute_b32 v23, v31, v17
	ds_bpermute_b32 v22, v31, v16
	s_waitcnt lgkmcnt(0)
	v_pk_add_f32 v[16:17], v[16:17], v[22:23]
	ds_bpermute_b32 v23, v32, v17
	ds_bpermute_b32 v22, v32, v16
	s_waitcnt lgkmcnt(0)
	v_pk_add_f32 v[16:17], v[16:17], v[22:23]
	ds_bpermute_b32 v23, v33, v17
	ds_bpermute_b32 v22, v33, v16
	s_waitcnt lgkmcnt(0)
	v_pk_add_f32 v[16:17], v[16:17], v[22:23]
	s_nop 0
	v_pk_fma_f32 v[16:17], v[16:17], s[2:3], v[18:19] op_sel_hi:[1,0,0]
	s_lshl_b32 s2, s26, 2
	s_add_u32 s2, s21, s2
	s_addc_u32 s3, s22, 0
	global_load_dword v120, v24, s[2:3]
	global_load_dword v121, v24, s[2:3] offset:64
	global_load_dword v122, v24, s[2:3] offset:128
	global_load_dword v123, v24, s[2:3] offset:192
	s_waitcnt vmcnt(3)
	v_mov_b32_e32 v25, v120
	v_mul_f32_e32 v18, 0x4b800000, v17
	v_cmp_gt_f32_e64 s[4:5], s33, v17
	v_cmp_gt_f32_e32 vcc, s33, v16
	s_lshl_b32 s92, s26, 1
	v_cndmask_b32_e64 v17, v17, v18, s[4:5]
	v_rsq_f32_e32 v17, v17
	s_add_i32 s25, s25, s90
	s_add_i32 s24, s24, s30
	v_mul_f32_e32 v18, 0x45800000, v17
	v_cndmask_b32_e64 v22, v17, v18, s[4:5]
	v_mul_f32_e32 v17, 0x4b800000, v16
	v_cndmask_b32_e32 v16, v16, v17, vcc
	v_rsq_f32_e32 v16, v16
	v_readlane_b32 s4, v253, 12
	v_readlane_b32 s5, v253, 13
	v_mul_f32_e32 v14, v14, v22
	v_mul_f32_e32 v17, 0x45800000, v16
	v_cndmask_b32_e32 v23, v16, v17, vcc
	v_lshlrev_b64 v[16:17], 12, v[80:81]
	v_lshl_add_u64 v[16:17], s[4:5], 0, v[16:17]
	v_lshl_add_u64 v[16:17], v[16:17], 0, s[92:93]
	v_lshl_add_u64 v[16:17], v[16:17], 0, v[176:177]
	s_nop 0
	v_mul_f32_e32 v12, v12, v25
	v_cvt_pk_bf16_f32 v12, v12, s0
	global_store_short v[16:17], v12, off offset:2048
	v_mul_f32_e32 v12, v13, v21
	v_mul_f32_e32 v12, v25, v12
	v_cvt_pk_bf16_f32 v18, v12, s0
	v_add_co_u32_e32 v12, vcc, s7, v16
	v_mul_f32_e32 v14, v25, v14
	s_nop 0
	v_addc_co_u32_e32 v13, vcc, 0, v17, vcc
	global_store_short v[12:13], v18, off offset:2048
	v_add_co_u32_e32 v18, vcc, s31, v16
	v_cvt_pk_bf16_f32 v14, v14, s0
	s_nop 0
	v_addc_co_u32_e32 v19, vcc, 0, v17, vcc
	global_store_short v[18:19], v14, off offset:2048
	v_mul_f32_e32 v14, v15, v23
	v_mul_f32_e32 v14, v25, v14
	v_cvt_pk_bf16_f32 v25, v14, s0
	v_add_co_u32_e32 v14, vcc, s35, v16
	s_nop 1
	v_addc_co_u32_e32 v15, vcc, 0, v17, vcc
	global_store_short v[14:15], v25, off offset:2048
	s_waitcnt vmcnt(6)
	v_mov_b32_e32 v25, v121
	s_nop 0
	v_mul_f32_e32 v8, v8, v25
	v_cvt_pk_bf16_f32 v8, v8, s0
	global_store_short v[16:17], v8, off offset:2080
	v_mul_f32_e32 v8, v9, v21
	v_mul_f32_e32 v8, v8, v25
	v_cvt_pk_bf16_f32 v8, v8, s0
	global_store_short v[12:13], v8, off offset:2080
	v_mul_f32_e32 v8, v10, v22
	v_mul_f32_e32 v8, v25, v8
	v_cvt_pk_bf16_f32 v8, v8, s0
	global_store_short v[18:19], v8, off offset:2080
	v_mul_f32_e32 v8, v11, v23
	v_mul_f32_e32 v8, v25, v8
	v_cvt_pk_bf16_f32 v8, v8, s0
	global_store_short v[14:15], v8, off offset:2080
	s_waitcnt vmcnt(9)
	v_mov_b32_e32 v8, v122
	s_nop 0
	v_mul_f32_e32 v4, v4, v8
	v_cvt_pk_bf16_f32 v4, v4, s0
	global_store_short v[16:17], v4, off offset:2112
	v_mul_f32_e32 v4, v5, v21
	v_mul_f32_e32 v4, v4, v8
	v_cvt_pk_bf16_f32 v4, v4, s0
	global_store_short v[12:13], v4, off offset:2112
	v_mul_f32_e32 v4, v6, v22
	v_mul_f32_e32 v4, v4, v8
	v_cvt_pk_bf16_f32 v4, v4, s0
	global_store_short v[18:19], v4, off offset:2112
	v_mul_f32_e32 v4, v7, v23
	v_mul_f32_e32 v4, v4, v8
	v_cvt_pk_bf16_f32 v4, v4, s0
	global_store_short v[14:15], v4, off offset:2112
	s_waitcnt vmcnt(12)
	v_mov_b32_e32 v4, v123
	v_readlane_b32 s2, v254, 61
	s_add_i32 s23, s23, s2
	s_cmpk_gt_i32 s25, 0x3ff
	s_nop 0
	v_mul_f32_e32 v0, v0, v4
	v_cvt_pk_bf16_f32 v0, v0, s0
	global_store_short v[16:17], v0, off offset:2144
	v_mul_f32_e32 v0, v1, v21
	v_mul_f32_e32 v0, v0, v4
	v_cvt_pk_bf16_f32 v0, v0, s0
	global_store_short v[12:13], v0, off offset:2144
	v_mul_f32_e32 v0, v2, v22
	v_mul_f32_e32 v0, v0, v4
	v_cvt_pk_bf16_f32 v0, v0, s0
	global_store_short v[18:19], v0, off offset:2144
	v_mul_f32_e32 v0, v3, v23
	v_mul_f32_e32 v0, v0, v4
	v_cvt_pk_bf16_f32 v0, v0, s0
	global_store_short v[14:15], v0, off offset:2144
	s_cbranch_scc1 .LBB0_270
